# pool GEMM: K range restricted to the 256 columns where the block-diagonal weight is non-zero for the tile (4 K-steps instead of 8)
# speedup vs baseline: 1.0040x; 1.0040x over previous
; #define PG8_STAGE(bufoff, gbase, voff) do { _Pragma("unroll") for (int _i = 0; _i < 2; ++_i) \
;         __builtin_amdgcn_global_load_lds((const unsigned*)((const char*)(gbase) + (voff)[_i]), (LAS unsigned*)(lds + (bufoff) + ldsw + _i * 8192), 16, 0, 0); } while (0)
; #define PG8_WAIT_V(n) asm volatile("s_waitcnt vmcnt(" #n ")" ::: "memory")
; #define PG8_BAR __builtin_amdgcn_s_barrier()
;     __device__ bool next(int i, Unit& u) const {
;         const long L = (long)i * G + c; if (L >= nwg) return false;
;         int wgid = (int)L; { const int q = nwg / NXCD, r = nwg % NXCD, xcd = wgid % NXCD, off = wgid / NXCD; wgid = (xcd < r ? xcd * (q + 1) : r * (q + 1) + (xcd - r) * q) + off; }
;         const int nig = WGM * nN, gid = wgid / nig, fm = gid * WGM, gsz = (nM - fm) < WGM ? (nM - fm) : WGM;
;         u.pm = fm + ((wgid % nig) % gsz); u.pn = (wgid % nig) / gsz; return true;
;     ...
;     for (int i = 0; i < 2; ++i) { int R, C; stage_rc(tid * 16 + i * 8192, R, C); const int Rb = Epi::PERM ? ((R & ~31) + perm32(R & 31)) : R;
;         voffA[i] = (unsigned)(R * lda + C) * 2u; voffB[i] = (unsigned)(Rb * ldb + C) * 2u; }
;     const size_t kstep = (size_t)(BK * 2);
;     const size_t hA = (size_t)HALF * lda * 2, hB = (size_t)HALF * ldb * 2;
;     const size_t tA = 2 * hA, tB = 2 * hB;
;     const unsigned ldsw = (unsigned)wid * 1024u;
;     const int aoff = lds_byte(wr * 64 + fr, fq * 8), boff = lds_byte(wc * 32 + fr, fq * 8);
;     ...
;     Unit cur, nxt; int ui = 0;
;     if (!S.next(0, cur)) return;
;     ...
;     f32x4 acc[2][2][4][2];
; #pragma unroll
;     for (int a = 0; a < 2; ++a)
; #pragma unroll
;         for (int b = 0; b < 2; ++b)
; #pragma unroll
;             for (int m = 0; m < 4; ++m)
; #pragma unroll
;                 for (int n = 0; n < 2; ++n) acc[a][b][m][n] = (f32x4){0.f, 0.f, 0.f, 0.f};
;     bf16x8 At[4][2], B0[2][2], B1[2][2];
;     const char* cA = (const char*)g.A + (size_t)cur.pm * tA; const char* cB = (const char*)g.Bt + (size_t)cur.pn * tB;
;     PG8_A_READY(cur);
;     PG8_STAGE(PG8_SB(0, 0), cB, voffB); PG8_STAGE(PG8_SA(0, 0), cA, voffA); PG8_STAGE(PG8_SB(0, 1), cB + hB, voffB); PG8_STAGE(PG8_SA(0, 1), cA + hA, voffA);
;     if (wr == 1) PG8_BAR;
;     PG8_WAIT_V(4); PG8_BAR;
;     PG8_STAGE(PG8_SB(1, 0), cB + kstep, voffB); PG8_STAGE(PG8_SA(1, 0), cA + kstep, voffA); PG8_STAGE(PG8_SB(1, 1), cB + hB + kstep, voffB);
.LBB0_337:
	s_abs_i32 s6, s51
	s_waitcnt vmcnt(0)
	v_cvt_f32_u32_e32 v0, s6
	s_sub_i32 s9, 0, s6
	s_add_i32 s7, s53, 0x88
	s_ashr_i32 s8, s7, 31
	v_rcp_iflag_f32_e32 v0, v0
	s_abs_i32 s7, s7
	s_load_dwordx2 s[10:11], s[0:1], 0x120
	s_waitcnt lgkmcnt(0)
	s_load_dwordx2 s[12:13], s[0:1], 0xf0
	s_waitcnt lgkmcnt(0)
	v_mul_f32_e32 v0, 0x4f7ffffe, v0
	v_cvt_u32_f32_e32 v0, v0
	s_load_dwordx2 s[14:15], s[0:1], 0x130
	s_waitcnt lgkmcnt(0)
	s_load_dwordx2 s[16:17], s[0:1], 0xa0
	s_waitcnt lgkmcnt(0)
	v_mov_b32_e32 v8, v166
	v_readfirstlane_b32 s18, v0
	s_mul_i32 s9, s9, s18
	s_mul_hi_u32 s9, s18, s9
	s_add_i32 s18, s18, s9
	s_mul_hi_u32 s9, s7, s18
	s_mul_i32 s9, s9, s6
	s_sub_i32 s7, s7, s9
	s_sub_i32 s9, s7, s6
	s_cmp_ge_u32 s7, s6
	s_cselect_b32 s7, s9, s7
	s_sub_i32 s9, s7, s6
	s_cmp_ge_u32 s7, s6
	s_cselect_b32 s6, s9, s7
	s_xor_b32 s6, s6, s8
	s_sub_i32 s38, s6, s8
	s_cmpk_gt_i32 s38, 0x87
	v_readfirstlane_b32 s39, v8
	s_cbranch_scc1 .LBB0_349
	v_lshlrev_b32_e32 v0, 4, v8
	v_add_u32_e32 v1, 0x2000, v0
	v_ashrrev_i32_e32 v2, 31, v1
	v_lshrrev_b32_e32 v2, 22, v2
	v_add_u32_e32 v2, v1, v2
	v_ashrrev_i32_e32 v9, 10, v2
	v_mul_i32_i24_e32 v2, 0x400, v9
	v_sub_u32_e32 v1, v1, v2
	v_lshrrev_b32_e32 v2, 4, v1
	v_bitop3_b32 v1, v2, v1, 32 bitop3:0x6c
	v_ashrrev_i32_e32 v2, 31, v1
	v_lshrrev_b32_e32 v2, 26, v2
	v_add_u32_e32 v2, v1, v2
	v_lshlrev_b32_e32 v3, 3, v9
	v_ashrrev_i32_e32 v10, 6, v2
	v_and_b32_e32 v3, -16, v3
	v_add_u32_e32 v3, v10, v3
	v_and_b32_e32 v4, 3, v10
	s_mov_b32 s8, 0x3fffe0
	v_lshrrev_b32_e32 v5, 2, v3
	v_lshlrev_b32_e32 v6, 1, v3
	v_and_b32_e32 v2, 0xc0, v2
	v_and_or_b32 v4, v3, s8, v4
	v_and_b32_e32 v5, 4, v5
	v_and_b32_e32 v6, 24, v6
	v_sub_u32_e32 v1, v1, v2
	v_mov_b32_e32 v2, 1
	v_or3_b32 v4, v4, v5, v6
	v_lshlrev_b32_e32 v5, 5, v9
	v_ashrrev_i16_sdwa v1, v2, sext(v1) dst_sel:DWORD dst_unused:UNUSED_PAD src0_sel:DWORD src1_sel:BYTE_0
	v_and_b32_e32 v5, 32, v5
	v_bfe_i32 v11, v1, 0, 16
	v_add_lshl_u32 v1, v5, v11, 1
	v_lshl_add_u32 v146, v4, 10, v1
	v_lshl_add_u32 v148, v3, 10, v1
	v_bfe_i32 v1, v8, 27, 1
	v_lshrrev_b32_e32 v1, 22, v1
	v_add_u32_e32 v1, v0, v1
	v_and_b32_e32 v1, 0xfffffc00, v1
	v_sub_u32_e32 v0, v0, v1
	v_lshrrev_b32_e32 v1, 4, v0
	v_ashrrev_i32_e32 v3, 31, v8
	v_bitop3_b32 v0, v1, v0, 32 bitop3:0x6c
	v_lshrrev_b32_e32 v3, 26, v3
	v_ashrrev_i32_e32 v1, 31, v0
	v_add_u32_e32 v3, v8, v3
	v_lshrrev_b32_e32 v1, 26, v1
	v_ashrrev_i32_e32 v13, 6, v3
	v_add_u32_e32 v1, v0, v1
	v_lshlrev_b32_e32 v3, 3, v13
	v_ashrrev_i32_e32 v12, 6, v1
	v_and_b32_e32 v3, -16, v3
	v_add_u32_e32 v3, v12, v3
	v_and_b32_e32 v4, 3, v12
	s_ashr_i32 s41, s38, 31
	v_and_or_b32 v4, v3, s8, v4
	s_lshr_b32 s8, s41, 29
	s_add_i32 s8, s38, s8
	s_ashr_i32 s6, s39, 6
	s_ashr_i32 s9, s8, 3
	s_and_b32 s8, s8, -8
	s_ashr_i32 s7, s39, 8
	s_lshl_b32 s40, s6, 10
	s_sub_i32 s8, s38, s8
	s_cmp_lt_i32 s8, 0
	s_cselect_b32 s18, 18, 17
	s_mul_i32 s8, s18, s8
	s_add_i32 s8, s8, s9
	s_ashr_i32 s9, s8, 31
	s_lshr_b32 s9, s9, 28
	s_add_i32 s9, s8, s9
	v_lshrrev_b32_e32 v5, 2, v3
	v_lshlrev_b32_e32 v6, 1, v3
	v_and_b32_e32 v1, 0xc0, v1
	s_ashr_i32 s18, s9, 4
	v_and_b32_e32 v5, 4, v5
	v_and_b32_e32 v6, 24, v6
	v_sub_u32_e32 v0, v0, v1
	s_lshl_b32 s18, s18, 3
	v_or3_b32 v4, v4, v5, v6
	v_lshlrev_b32_e32 v5, 5, v13
	v_ashrrev_i16_sdwa v0, v2, sext(v0) dst_sel:DWORD dst_unused:UNUSED_PAD src0_sel:DWORD src1_sel:BYTE_0
	s_sub_i32 s19, 0x44, s18
	v_and_b32_e32 v5, 32, v5
	v_bfe_i32 v14, v0, 0, 16
	s_min_u32 s19, s19, 8
	s_and_b32 s9, s9, -16
	v_add_lshl_u32 v0, v5, v14, 1
	s_sub_i32 s20, s8, s9
	v_cvt_f32_ubyte0_e32 v2, s19
	v_lshl_add_u32 v150, v4, 10, v0
	v_cvt_f32_i32_e32 v1, s20
	v_rcp_iflag_f32_e32 v4, v2
	v_lshl_add_u32 v152, v3, 10, v0
	s_ashr_i32 s8, s20, 30
	s_or_b32 s21, s8, 1
	v_mul_f32_e32 v0, v1, v4
	v_trunc_f32_e32 v0, v0
	v_fma_f32 v1, -v0, v2, v1
	v_cvt_i32_f32_e32 v0, v0
	v_cmp_ge_f32_e64 s[8:9], |v1|, v2
	s_and_b64 s[8:9], s[8:9], exec
	s_cselect_b32 s8, s21, 0
	v_readfirstlane_b32 s9, v0
	s_add_i32 s8, s9, s8
	s_mul_i32 s9, s8, s19
	s_sub_i32 s9, s20, s9
	s_sext_i32_i8 s9, s9
	s_add_i32 s28, s18, s9
	s_ashr_i32 s29, s28, 31
	s_bfe_i64 s[20:21], s[8:9], 0x80000
	s_lshl_b64 s[18:19], s[28:29], 18
	s_lshl_b64 s[20:21], s[20:21], 18
	s_lshr_b32 s98, s20, 9
	s_add_u32 s20, s20, s98
	s_add_u32 s18, s18, s98
	s_add_u32 s30, s12, s20
	s_addc_u32 s31, s13, s21
	s_add_i32 s29, s40, 0
	s_add_i32 m0, s29, 0x10000
	v_mov_b32_e32 v151, 0
	global_load_lds_dwordx4 v150, s[30:31]
	s_add_i32 m0, s29, 0x12000
	s_add_u32 s34, s10, s18
	global_load_lds_dwordx4 v146, s[30:31]
	s_addc_u32 s35, s11, s19
	s_mov_b32 m0, s29
	s_add_i32 s53, s29, 0x2000
	global_load_lds_dwordx4 v152, s[34:35]
	s_mov_b32 m0, s53
	s_add_u32 s18, s30, 0x20000
	global_load_lds_dwordx4 v148, s[34:35]
	s_addc_u32 s19, s31, 0
	s_add_i32 m0, s29, 0x14000
	v_mov_b32_e32 v147, v151
	global_load_lds_dwordx4 v150, s[18:19]
	s_add_i32 m0, s29, 0x16000
	v_mov_b32_e32 v153, v151
	global_load_lds_dwordx4 v146, s[18:19]
	s_add_u32 s18, s34, 0x20000
	s_addc_u32 s19, s35, 0
	s_add_i32 s56, s29, 0x4000
	s_mov_b32 m0, s56
	s_add_i32 s57, s29, 0x6000
	global_load_lds_dwordx4 v152, s[18:19]
	s_mov_b32 m0, s57
	v_mov_b32_e32 v149, v151
	global_load_lds_dwordx4 v148, s[18:19]
	v_lshl_add_u64 v[6:7], s[30:31], 0, v[150:151]
	v_lshl_add_u64 v[4:5], s[30:31], 0, v[146:147]
	v_lshl_add_u64 v[2:3], s[34:35], 0, v[152:153]
	s_cmp_lg_u32 s7, 1
	v_lshl_add_u64 v[0:1], s[34:35], 0, v[148:149]
	s_cbranch_scc1 .LBB0_340
	s_barrier

; #define PG8_STAGE(bufoff, gbase, voff) do { _Pragma("unroll") for (int _i = 0; _i < 2; ++_i) \
;         __builtin_amdgcn_global_load_lds((const unsigned*)((const char*)(gbase) + (voff)[_i]), (LAS unsigned*)(lds + (bufoff) + ldsw + _i * 8192), 16, 0, 0); } while (0)
; #define PG8_LDA(dst, b, h) do { _Pragma("unroll") for (int m = 0; m < 4; ++m) _Pragma("unroll") for (int k = 0; k < 2; ++k) dst[m][k] = *(const LAS bf16x8*)(lds + PG8_SA(b, h) + aoff + m * 2048 + k * 1024); } while (0)
; #define PG8_LDB(dst, b, h) do { _Pragma("unroll") for (int n = 0; n < 2; ++n) _Pragma("unroll") for (int k = 0; k < 2; ++k) dst[n][k] = *(const LAS bf16x8*)(lds + PG8_SB(b, h) + boff + n * 2048 + k * 1024); } while (0)
; #define PG8_MMA(ai, bj, At, Bt) do { __builtin_amdgcn_s_setprio(1); _Pragma("unroll") for (int m = 0; m < 4; ++m) _Pragma("unroll") for (int n = 0; n < 2; ++n) _Pragma("unroll") for (int k = 0; k < 2; ++k) \
;         acc[ai][bj][m][n] = __builtin_amdgcn_mfma_f32_16x16x32_bf16(Bt[n][k], At[m][k], acc[ai][bj][m][n], 0, 0, 0); __builtin_amdgcn_s_setprio(0); } while (0)
; #define PG8_WAIT_L(n) asm volatile("s_waitcnt lgkmcnt(" #n ")" ::: "memory")
; #define PG8_BAR __builtin_amdgcn_s_barrier()
; #define PG8_SCHED __builtin_amdgcn_sched_barrier(0)
;     ...
;         const bool has_next = S.next(ui + 1, nxt);
;         const char* nA = has_next ? (const char*)g.A + (size_t)nxt.pm * tA : cA; const char* nB = has_next ? (const char*)g.Bt + (size_t)nxt.pn * tB : cB;
; #pragma unroll 1
;         for (int t = 0; t < nt; t += 2) {
;             const bool last = (t == nt - 2);
;             const char* a1 = cA + (size_t)(t + 1) * kstep;
;             const char* a2 = last ? nA : cA + (size_t)(t + 2) * kstep; const char* b2 = last ? nB : cB + (size_t)(t + 2) * kstep;
;             const char* a3 = a2 + kstep; const char* b3 = b2 + kstep;
;             if (last && has_next) PG8_A_READY(nxt);
;             PG8_LDB(B0, 0, 0); PG8_SCHED; PG8_LDA(At, 0, 0); PG8_STAGE(PG8_SA(1, 1), a1 + hA, voffA);
;             PG8_WAIT_L(8); PG8_BAR; PG8_WAIT_L(0); PG8_MMA(0, 0, At, B0); PG8_BAR; PG8_SCHED;
;     ...
;         for (int a = 0; a < 2; ++a)
; #pragma unroll
;             for (int b = 0; b < 2; ++b)
; #pragma unroll
;                 for (int m = 0; m < 4; ++m)
; #pragma unroll
;                     for (int n = 0; n < 2; ++n) acc[a][b][m][n] = (f32x4){0.f, 0.f, 0.f, 0.f};
.LBB0_343:
	s_ashr_i32 s23, s22, 31
	v_cmp_lt_i64_e32 vcc, s[24:25], v[158:159]
	s_lshl_b64 s[24:25], s[22:23], 18
	s_lshl_b32 s98, s20, 9
	s_add_u32 s24, s24, s98
	s_add_u32 s24, s10, s24
	s_addc_u32 s25, s11, s25
	s_and_b64 s[26:27], vcc, exec
	s_cselect_b32 s7, s25, s35
	s_cselect_b32 s23, s24, s34
	s_ashr_i32 s21, s20, 31
	s_lshl_b64 s[26:27], s[20:21], 18
	s_add_u32 s26, s26, s98
	s_add_u32 s26, s12, s26
	s_addc_u32 s27, s13, s27
	s_and_b64 s[36:37], vcc, exec
	s_cselect_b32 s21, s27, s31
	s_cselect_b32 s33, s26, s30
	s_add_u32 s42, s30, 0x100
	s_addc_u32 s43, s31, 0
	s_add_u32 s30, s34, 0x20080
	v_mov_b32_e32 v0, 0
	s_addc_u32 s31, s35, 0
	s_mov_b32 s44, -2
	v_mov_b32_e32 v1, v0
	v_mov_b32_e32 v2, v0
	v_mov_b32_e32 v3, v0
	v_mov_b32_e32 v4, v0
	v_mov_b32_e32 v5, v0
	v_mov_b32_e32 v6, v0
	v_mov_b32_e32 v7, v0
	v_mov_b32_e32 v12, v0
	v_mov_b32_e32 v13, v0
	v_mov_b32_e32 v14, v0
	v_mov_b32_e32 v15, v0
	v_mov_b32_e32 v20, v0
	v_mov_b32_e32 v21, v0
	v_mov_b32_e32 v22, v0
	v_mov_b32_e32 v23, v0
	v_mov_b32_e32 v28, v0
	v_mov_b32_e32 v29, v0
	v_mov_b32_e32 v30, v0
	v_mov_b32_e32 v31, v0
	v_mov_b32_e32 v36, v0
	v_mov_b32_e32 v37, v0
	v_mov_b32_e32 v38, v0
	v_mov_b32_e32 v39, v0
	v_mov_b32_e32 v44, v0
	v_mov_b32_e32 v45, v0
	v_mov_b32_e32 v46, v0
	v_mov_b32_e32 v47, v0
	v_mov_b32_e32 v52, v0
	v_mov_b32_e32 v53, v0
	v_mov_b32_e32 v54, v0
	v_mov_b32_e32 v55, v0
	v_mov_b32_e32 v8, v0
	v_mov_b32_e32 v9, v0
	v_mov_b32_e32 v10, v0
	v_mov_b32_e32 v11, v0
	v_mov_b32_e32 v16, v0
	v_mov_b32_e32 v17, v0
	v_mov_b32_e32 v18, v0
	v_mov_b32_e32 v19, v0
	v_mov_b32_e32 v24, v0
	v_mov_b32_e32 v25, v0
	v_mov_b32_e32 v26, v0
	v_mov_b32_e32 v27, v0
	v_mov_b32_e32 v32, v0
	v_mov_b32_e32 v33, v0
	v_mov_b32_e32 v34, v0
	v_mov_b32_e32 v35, v0
	v_mov_b32_e32 v40, v0
	v_mov_b32_e32 v41, v0
	v_mov_b32_e32 v42, v0
	v_mov_b32_e32 v43, v0
	v_mov_b32_e32 v48, v0
	v_mov_b32_e32 v49, v0
	v_mov_b32_e32 v50, v0
	v_mov_b32_e32 v51, v0
	v_mov_b32_e32 v56, v0
	v_mov_b32_e32 v57, v0
	v_mov_b32_e32 v58, v0
	v_mov_b32_e32 v59, v0
	v_mov_b32_e32 v60, v0
	v_mov_b32_e32 v61, v0
	v_mov_b32_e32 v62, v0
	v_mov_b32_e32 v63, v0
	v_mov_b32_e32 v64, v0
	v_mov_b32_e32 v65, v0
	v_mov_b32_e32 v66, v0
	v_mov_b32_e32 v67, v0
	v_mov_b32_e32 v68, v0
	v_mov_b32_e32 v69, v0
	v_mov_b32_e32 v70, v0
	v_mov_b32_e32 v71, v0
	v_mov_b32_e32 v72, v0
	v_mov_b32_e32 v73, v0
	v_mov_b32_e32 v74, v0
	v_mov_b32_e32 v75, v0
	v_mov_b32_e32 v76, v0
	v_mov_b32_e32 v77, v0
	v_mov_b32_e32 v78, v0
	v_mov_b32_e32 v79, v0
	v_mov_b32_e32 v84, v0
	v_mov_b32_e32 v85, v0
	v_mov_b32_e32 v86, v0
	v_mov_b32_e32 v87, v0
	v_mov_b32_e32 v88, v0
	v_mov_b32_e32 v89, v0
	v_mov_b32_e32 v90, v0
	v_mov_b32_e32 v91, v0
	v_mov_b32_e32 v96, v0
	v_mov_b32_e32 v97, v0
	v_mov_b32_e32 v98, v0
	v_mov_b32_e32 v99, v0
	v_mov_b32_e32 v104, v0
	v_mov_b32_e32 v105, v0
	v_mov_b32_e32 v106, v0
	v_mov_b32_e32 v107, v0
	v_mov_b32_e32 v80, v0
	v_mov_b32_e32 v81, v0
	v_mov_b32_e32 v82, v0
	v_mov_b32_e32 v83, v0
	v_mov_b32_e32 v92, v0
	v_mov_b32_e32 v93, v0
	v_mov_b32_e32 v94, v0
	v_mov_b32_e32 v95, v0
	v_mov_b32_e32 v100, v0
	v_mov_b32_e32 v101, v0
	v_mov_b32_e32 v102, v0
	v_mov_b32_e32 v103, v0
	v_mov_b32_e32 v108, v0
	v_mov_b32_e32 v109, v0
	v_mov_b32_e32 v110, v0
	v_mov_b32_e32 v111, v0
	v_mov_b32_e32 v112, v0
	v_mov_b32_e32 v113, v0
	v_mov_b32_e32 v114, v0
	v_mov_b32_e32 v115, v0
	v_mov_b32_e32 v116, v0
	v_mov_b32_e32 v117, v0
	v_mov_b32_e32 v118, v0
	v_mov_b32_e32 v119, v0
	v_mov_b32_e32 v120, v0
	v_mov_b32_e32 v121, v0
	v_mov_b32_e32 v122, v0
	v_mov_b32_e32 v123, v0
	v_mov_b32_e32 v124, v0
	v_mov_b32_e32 v125, v0
	v_mov_b32_e32 v126, v0
	v_mov_b32_e32 v127, v0
.LBB0_344:
	ds_read_b128 v[128:131], v173
	ds_read_b128 v[132:135], v173 offset:1024
	ds_read_b128 v[136:139], v173 offset:2048
	ds_read_b128 v[140:143], v173 offset:3072
	s_add_u32 s34, s30, 0xfffe0080
	s_addc_u32 s35, s31, -1
	s_cmp_eq_u32 s44, 0
	s_cselect_b32 s37, s7, s35
	s_cselect_b32 s36, s23, s34
	s_cselect_b32 s35, s21, s43
	s_cselect_b32 s34, s33, s42
	v_lshl_add_u64 v[204:205], s[30:31], 0, v[156:157]
	s_add_i32 m0, s29, 0xc000
	ds_read_b128 v[162:165], v174
	ds_read_b128 v[176:179], v174 offset:1024
	ds_read_b128 v[180:183], v174 offset:2048
	ds_read_b128 v[184:187], v174 offset:3072
	ds_read_b128 v[188:191], v174 offset:4096
	ds_read_b128 v[192:195], v174 offset:5120
	ds_read_b128 v[196:199], v174 offset:6144
	ds_read_b128 v[200:203], v174 offset:7168
	global_load_lds_dwordx4 v[204:205], off
	v_lshl_add_u64 v[204:205], s[30:31], 0, v[154:155]
	s_add_i32 m0, s29, 0xe000
	s_nop 0
	global_load_lds_dwordx4 v[204:205], off
	s_waitcnt lgkmcnt(8)
	s_barrier
	s_waitcnt lgkmcnt(0)
	s_setprio 1
	s_waitcnt lgkmcnt(0)
	v_mfma_f32_16x16x32_bf16 v[124:127], v[128:131], v[162:165], v[124:127]
	v_mfma_f32_16x16x32_bf16 v[120:123], v[136:139], v[162:165], v[120:123]
	v_mfma_f32_16x16x32_bf16 v[116:119], v[128:131], v[180:183], v[116:119]
	v_mfma_f32_16x16x32_bf16 v[112:115], v[136:139], v[180:183], v[112:115]
	v_mfma_f32_16x16x32_bf16 v[108:111], v[128:131], v[188:191], v[108:111]
	v_mfma_f32_16x16x32_bf16 v[100:103], v[136:139], v[188:191], v[100:103]
	v_mfma_f32_16x16x32_bf16 v[92:95], v[128:131], v[196:199], v[92:95]
	v_mfma_f32_16x16x32_bf16 v[80:83], v[136:139], v[196:199], v[80:83]
	v_mfma_f32_16x16x32_bf16 v[124:127], v[132:135], v[176:179], v[124:127]
	v_mfma_f32_16x16x32_bf16 v[120:123], v[140:143], v[176:179], v[120:123]
	v_mfma_f32_16x16x32_bf16 v[116:119], v[132:135], v[184:187], v[116:119]
	v_mfma_f32_16x16x32_bf16 v[112:115], v[140:143], v[184:187], v[112:115]
	v_mfma_f32_16x16x32_bf16 v[108:111], v[132:135], v[192:195], v[108:111]
	v_mfma_f32_16x16x32_bf16 v[100:103], v[140:143], v[192:195], v[100:103]
	v_mfma_f32_16x16x32_bf16 v[92:95], v[132:135], v[200:203], v[92:95]
	v_mfma_f32_16x16x32_bf16 v[80:83], v[140:143], v[200:203], v[80:83]
	s_setprio 0
	s_barrier
; #define PG8_STAGE(bufoff, gbase, voff) do { _Pragma("unroll") for (int _i = 0; _i < 2; ++_i) \
;         __builtin_amdgcn_global_load_lds((const unsigned*)((const char*)(gbase) + (voff)[_i]), (LAS unsigned*)(lds + (bufoff) + ldsw + _i * 8192), 16, 0, 0); } while (0)
; #define PG8_LDA(dst, b, h) do { _Pragma("unroll") for (int m = 0; m < 4; ++m) _Pragma("unroll") for (int k = 0; k < 2; ++k) dst[m][k] = *(const LAS bf16x8*)(lds + PG8_SA(b, h) + aoff + m * 2048 + k * 1024); } while (0)
; #define PG8_LDB(dst, b, h) do { _Pragma("unroll") for (int n = 0; n < 2; ++n) _Pragma("unroll") for (int k = 0; k < 2; ++k) dst[n][k] = *(const LAS bf16x8*)(lds + PG8_SB(b, h) + boff + n * 2048 + k * 1024); } while (0)
; #define PG8_MMA(ai, bj, At, Bt) do { __builtin_amdgcn_s_setprio(1); _Pragma("unroll") for (int m = 0; m < 4; ++m) _Pragma("unroll") for (int n = 0; n < 2; ++n) _Pragma("unroll") for (int k = 0; k < 2; ++k) \
;         acc[ai][bj][m][n] = __builtin_amdgcn_mfma_f32_16x16x32_bf16(Bt[n][k], At[m][k], acc[ai][bj][m][n], 0, 0, 0); __builtin_amdgcn_s_setprio(0); } while (0)
; #define PG8_WAIT_V(n) asm volatile("s_waitcnt vmcnt(" #n ")" ::: "memory")
; #define PG8_WAIT_L(n) asm volatile("s_waitcnt lgkmcnt(" #n ")" ::: "memory")
; #define PG8_BAR __builtin_amdgcn_s_barrier()
; #define PG8_SCHED __builtin_amdgcn_sched_barrier(0)
;     ...
;             PG8_LDB(B1, 0, 1); PG8_STAGE(PG8_SB(0, 0), b2, voffB);
;             PG8_BAR; PG8_WAIT_L(0); PG8_MMA(0, 1, At, B1); PG8_BAR;
;             PG8_LDA(At, 0, 1); PG8_STAGE(PG8_SA(0, 0), a2, voffA);
;             PG8_BAR; PG8_WAIT_L(0); PG8_MMA(1, 0, At, B0); PG8_BAR; PG8_SCHED;
;             PG8_STAGE(PG8_SB(0, 1), b2 + hB, voffB);
;             PG8_WAIT_V(6); PG8_BAR; PG8_MMA(1, 1, At, B1); PG8_BAR;
;             PG8_LDB(B0, 1, 0); PG8_SCHED; PG8_LDA(At, 1, 0); PG8_STAGE(PG8_SA(0, 1), a2 + hA, voffA);
;             PG8_WAIT_L(8); PG8_BAR; PG8_WAIT_L(0); PG8_MMA(0, 0, At, B0); PG8_BAR; PG8_SCHED;
	s_add_i32 s45, s62, s40
	v_lshl_add_u64 v[220:221], s[34:35], 0, v[150:151]
	s_mov_b32 m0, s45
	ds_read_b128 v[204:207], v175
	ds_read_b128 v[208:211], v175 offset:1024
	ds_read_b128 v[212:215], v175 offset:2048
	ds_read_b128 v[216:219], v175 offset:3072
	global_load_lds_dwordx4 v[220:221], off
	v_lshl_add_u64 v[222:223], s[34:35], 0, v[146:147]
	s_add_i32 m0, s45, 0x2000
	s_nop 0
	global_load_lds_dwordx4 v[222:223], off
	s_barrier
	s_waitcnt lgkmcnt(0)
	s_setprio 1
	s_waitcnt lgkmcnt(0)
	v_mfma_f32_16x16x32_bf16 v[104:107], v[204:207], v[162:165], v[104:107]
	v_mfma_f32_16x16x32_bf16 v[96:99], v[212:215], v[162:165], v[96:99]
	v_mfma_f32_16x16x32_bf16 v[88:91], v[204:207], v[180:183], v[88:91]
	v_mfma_f32_16x16x32_bf16 v[84:87], v[212:215], v[180:183], v[84:87]
	v_mfma_f32_16x16x32_bf16 v[76:79], v[204:207], v[188:191], v[76:79]
	v_mfma_f32_16x16x32_bf16 v[72:75], v[212:215], v[188:191], v[72:75]
	v_mfma_f32_16x16x32_bf16 v[68:71], v[204:207], v[196:199], v[68:71]
	v_mfma_f32_16x16x32_bf16 v[64:67], v[212:215], v[196:199], v[64:67]
	v_mfma_f32_16x16x32_bf16 v[104:107], v[208:211], v[176:179], v[104:107]
	v_mfma_f32_16x16x32_bf16 v[96:99], v[216:219], v[176:179], v[96:99]
	v_mfma_f32_16x16x32_bf16 v[88:91], v[208:211], v[184:187], v[88:91]
	v_mfma_f32_16x16x32_bf16 v[84:87], v[216:219], v[184:187], v[84:87]
	v_mfma_f32_16x16x32_bf16 v[76:79], v[208:211], v[192:195], v[76:79]
	v_mfma_f32_16x16x32_bf16 v[72:75], v[216:219], v[192:195], v[72:75]
	v_mfma_f32_16x16x32_bf16 v[68:71], v[208:211], v[200:203], v[68:71]
	v_mfma_f32_16x16x32_bf16 v[64:67], v[216:219], v[200:203], v[64:67]
	s_setprio 0
	s_mov_b32 m0, s29
	v_lshl_add_u64 v[224:225], s[36:37], 0, v[152:153]
	s_barrier
	ds_read_b128 v[162:165], v174 offset:16384
	ds_read_b128 v[176:179], v174 offset:17408
	ds_read_b128 v[180:183], v174 offset:18432
	ds_read_b128 v[184:187], v174 offset:19456
	ds_read_b128 v[188:191], v174 offset:20480
	ds_read_b128 v[192:195], v174 offset:21504
	ds_read_b128 v[196:199], v174 offset:22528
	ds_read_b128 v[200:203], v174 offset:23552
	global_load_lds_dwordx4 v[224:225], off
	v_lshl_add_u64 v[226:227], s[36:37], 0, v[148:149]
	s_mov_b32 m0, s53
	s_nop 0
	global_load_lds_dwordx4 v[226:227], off
	s_barrier
	s_waitcnt lgkmcnt(0)
	s_setprio 1
	s_waitcnt lgkmcnt(0)
	v_mfma_f32_16x16x32_bf16 v[60:63], v[128:131], v[162:165], v[60:63]
	v_mfma_f32_16x16x32_bf16 v[56:59], v[136:139], v[162:165], v[56:59]
	v_mfma_f32_16x16x32_bf16 v[48:51], v[128:131], v[180:183], v[48:51]
	v_mfma_f32_16x16x32_bf16 v[40:43], v[136:139], v[180:183], v[40:43]
	v_mfma_f32_16x16x32_bf16 v[32:35], v[128:131], v[188:191], v[32:35]
	v_mfma_f32_16x16x32_bf16 v[24:27], v[136:139], v[188:191], v[24:27]
	v_mfma_f32_16x16x32_bf16 v[16:19], v[128:131], v[196:199], v[16:19]
	v_mfma_f32_16x16x32_bf16 v[8:11], v[136:139], v[196:199], v[8:11]
	v_mfma_f32_16x16x32_bf16 v[60:63], v[132:135], v[176:179], v[60:63]
	v_mfma_f32_16x16x32_bf16 v[56:59], v[140:143], v[176:179], v[56:59]
	v_mfma_f32_16x16x32_bf16 v[48:51], v[132:135], v[184:187], v[48:51]
	v_mfma_f32_16x16x32_bf16 v[40:43], v[140:143], v[184:187], v[40:43]
	v_mfma_f32_16x16x32_bf16 v[32:35], v[132:135], v[192:195], v[32:35]
	v_mfma_f32_16x16x32_bf16 v[24:27], v[140:143], v[192:195], v[24:27]
	v_mfma_f32_16x16x32_bf16 v[16:19], v[132:135], v[200:203], v[16:19]
	v_mfma_f32_16x16x32_bf16 v[8:11], v[140:143], v[200:203], v[8:11]
	s_setprio 0
	s_barrier
	s_add_u32 s66, s34, 0x20000
	s_addc_u32 s67, s35, 0
	s_add_i32 s45, s63, s40
	v_lshl_add_u64 v[128:129], s[66:67], 0, v[150:151]
	s_mov_b32 m0, s45
	s_nop 0
	global_load_lds_dwordx4 v[128:129], off
	v_lshl_add_u64 v[128:129], s[66:67], 0, v[146:147]
	s_add_i32 m0, s45, 0x2000
	s_nop 0
	global_load_lds_dwordx4 v[128:129], off
	s_waitcnt vmcnt(6)
	s_barrier
	s_setprio 1
	v_mfma_f32_16x16x32_bf16 v[52:55], v[204:207], v[162:165], v[52:55]
	v_mfma_f32_16x16x32_bf16 v[44:47], v[212:215], v[162:165], v[44:47]
	v_mfma_f32_16x16x32_bf16 v[36:39], v[204:207], v[180:183], v[36:39]
	v_mfma_f32_16x16x32_bf16 v[28:31], v[212:215], v[180:183], v[28:31]
	v_mfma_f32_16x16x32_bf16 v[20:23], v[204:207], v[188:191], v[20:23]
	v_mfma_f32_16x16x32_bf16 v[12:15], v[212:215], v[188:191], v[12:15]
	v_mfma_f32_16x16x32_bf16 v[4:7], v[204:207], v[196:199], v[4:7]
	v_mfma_f32_16x16x32_bf16 v[0:3], v[212:215], v[196:199], v[0:3]
	v_mfma_f32_16x16x32_bf16 v[52:55], v[208:211], v[176:179], v[52:55]
	v_mfma_f32_16x16x32_bf16 v[44:47], v[216:219], v[176:179], v[44:47]
	v_mfma_f32_16x16x32_bf16 v[36:39], v[208:211], v[184:187], v[36:39]
	v_mfma_f32_16x16x32_bf16 v[28:31], v[216:219], v[184:187], v[28:31]
	v_mfma_f32_16x16x32_bf16 v[20:23], v[208:211], v[192:195], v[20:23]
	v_mfma_f32_16x16x32_bf16 v[12:15], v[216:219], v[192:195], v[12:15]
	v_mfma_f32_16x16x32_bf16 v[4:7], v[208:211], v[200:203], v[4:7]
	v_mfma_f32_16x16x32_bf16 v[0:3], v[216:219], v[200:203], v[0:3]
	s_setprio 0
	s_add_i32 s45, 0, 0x18000
	v_add_u32_e32 v140, s45, v171
	s_barrier
	ds_read_b128 v[128:131], v140
	ds_read_b128 v[132:135], v140 offset:1024
	ds_read_b128 v[136:139], v140 offset:2048
	ds_read_b128 v[140:143], v140 offset:3072
	s_add_u32 s36, s36, 0x20000
	s_addc_u32 s37, s37, 0
	s_mov_b32 m0, s56
	v_lshl_add_u64 v[204:205], s[36:37], 0, v[152:153]
	ds_read_b128 v[162:165], v174 offset:32768
	ds_read_b128 v[176:179], v174 offset:33792
	ds_read_b128 v[180:183], v174 offset:34816
	ds_read_b128 v[184:187], v174 offset:35840
	ds_read_b128 v[188:191], v174 offset:36864
	ds_read_b128 v[192:195], v174 offset:37888
	ds_read_b128 v[196:199], v174 offset:38912
	ds_read_b128 v[200:203], v174 offset:39936
	global_load_lds_dwordx4 v[204:205], off
	v_lshl_add_u64 v[204:205], s[36:37], 0, v[148:149]
	s_mov_b32 m0, s57
	s_nop 0
	global_load_lds_dwordx4 v[204:205], off
	s_waitcnt lgkmcnt(8)
	s_barrier
; #define PG8_STAGE(bufoff, gbase, voff) do { _Pragma("unroll") for (int _i = 0; _i < 2; ++_i) \
;         __builtin_amdgcn_global_load_lds((const unsigned*)((const char*)(gbase) + (voff)[_i]), (LAS unsigned*)(lds + (bufoff) + ldsw + _i * 8192), 16, 0, 0); } while (0)
; #define PG8_LDA(dst, b, h) do { _Pragma("unroll") for (int m = 0; m < 4; ++m) _Pragma("unroll") for (int k = 0; k < 2; ++k) dst[m][k] = *(const LAS bf16x8*)(lds + PG8_SA(b, h) + aoff + m * 2048 + k * 1024); } while (0)
; #define PG8_LDB(dst, b, h) do { _Pragma("unroll") for (int n = 0; n < 2; ++n) _Pragma("unroll") for (int k = 0; k < 2; ++k) dst[n][k] = *(const LAS bf16x8*)(lds + PG8_SB(b, h) + boff + n * 2048 + k * 1024); } while (0)
; #define PG8_MMA(ai, bj, At, Bt) do { __builtin_amdgcn_s_setprio(1); _Pragma("unroll") for (int m = 0; m < 4; ++m) _Pragma("unroll") for (int n = 0; n < 2; ++n) _Pragma("unroll") for (int k = 0; k < 2; ++k) \
;         acc[ai][bj][m][n] = __builtin_amdgcn_mfma_f32_16x16x32_bf16(Bt[n][k], At[m][k], acc[ai][bj][m][n], 0, 0, 0); __builtin_amdgcn_s_setprio(0); } while (0)
; #define PG8_WAIT_V(n) asm volatile("s_waitcnt vmcnt(" #n ")" ::: "memory")
; #define PG8_WAIT_L(n) asm volatile("s_waitcnt lgkmcnt(" #n ")" ::: "memory")
; #define PG8_BAR __builtin_amdgcn_s_barrier()
; #define PG8_SCHED __builtin_amdgcn_sched_barrier(0)
;     ...
;             PG8_WAIT_L(8); PG8_BAR; PG8_WAIT_L(0); PG8_MMA(0, 0, At, B0); PG8_BAR; PG8_SCHED;
;             PG8_LDB(B1, 1, 1); PG8_STAGE(PG8_SB(1, 0), b3, voffB);
;             PG8_BAR; PG8_WAIT_L(0); PG8_MMA(0, 1, At, B1); PG8_BAR;
;             PG8_LDA(At, 1, 1); PG8_STAGE(PG8_SA(1, 0), a3, voffA);
;             PG8_BAR; PG8_WAIT_L(0); PG8_MMA(1, 0, At, B0); PG8_BAR; PG8_SCHED;
;             PG8_STAGE(PG8_SB(1, 1), b3 + hB, voffB);
;             PG8_WAIT_V(6); PG8_BAR; PG8_MMA(1, 1, At, B1); PG8_BAR;
	s_waitcnt lgkmcnt(0)
	s_setprio 1
	s_waitcnt lgkmcnt(0)
	v_mfma_f32_16x16x32_bf16 v[124:127], v[128:131], v[162:165], v[124:127]
	v_mfma_f32_16x16x32_bf16 v[120:123], v[136:139], v[162:165], v[120:123]
	v_mfma_f32_16x16x32_bf16 v[116:119], v[128:131], v[180:183], v[116:119]
	v_mfma_f32_16x16x32_bf16 v[112:115], v[136:139], v[180:183], v[112:115]
	v_mfma_f32_16x16x32_bf16 v[108:111], v[128:131], v[188:191], v[108:111]
	v_mfma_f32_16x16x32_bf16 v[100:103], v[136:139], v[188:191], v[100:103]
	v_mfma_f32_16x16x32_bf16 v[92:95], v[128:131], v[196:199], v[92:95]
	v_mfma_f32_16x16x32_bf16 v[80:83], v[136:139], v[196:199], v[80:83]
	v_mfma_f32_16x16x32_bf16 v[124:127], v[132:135], v[176:179], v[124:127]
	v_mfma_f32_16x16x32_bf16 v[120:123], v[140:143], v[176:179], v[120:123]
	v_mfma_f32_16x16x32_bf16 v[116:119], v[132:135], v[184:187], v[116:119]
	v_mfma_f32_16x16x32_bf16 v[112:115], v[140:143], v[184:187], v[112:115]
	v_mfma_f32_16x16x32_bf16 v[108:111], v[132:135], v[192:195], v[108:111]
	v_mfma_f32_16x16x32_bf16 v[100:103], v[140:143], v[192:195], v[100:103]
	v_mfma_f32_16x16x32_bf16 v[92:95], v[132:135], v[200:203], v[92:95]
	v_mfma_f32_16x16x32_bf16 v[80:83], v[140:143], v[200:203], v[80:83]
	s_setprio 0
	s_barrier
	s_add_i32 s36, 0, 0x1c000
	s_add_i32 s37, s45, s40
	v_add_u32_e32 v216, s36, v171
	v_lshl_add_u64 v[220:221], v[220:221], 0, s[18:19]
	s_mov_b32 m0, s37
	ds_read_b128 v[204:207], v216
	ds_read_b128 v[208:211], v216 offset:1024
	ds_read_b128 v[212:215], v216 offset:2048
	ds_read_b128 v[216:219], v216 offset:3072
	global_load_lds_dwordx4 v[220:221], off
	v_lshl_add_u64 v[220:221], v[222:223], 0, s[18:19]
	s_add_i32 m0, s37, 0x2000
	s_nop 0
	global_load_lds_dwordx4 v[220:221], off
	s_barrier
	s_waitcnt lgkmcnt(0)
	s_setprio 1
	s_waitcnt lgkmcnt(0)
	v_mfma_f32_16x16x32_bf16 v[104:107], v[204:207], v[162:165], v[104:107]
	v_mfma_f32_16x16x32_bf16 v[96:99], v[212:215], v[162:165], v[96:99]
	v_mfma_f32_16x16x32_bf16 v[88:91], v[204:207], v[180:183], v[88:91]
	v_mfma_f32_16x16x32_bf16 v[84:87], v[212:215], v[180:183], v[84:87]
	v_mfma_f32_16x16x32_bf16 v[76:79], v[204:207], v[188:191], v[76:79]
	v_mfma_f32_16x16x32_bf16 v[72:75], v[212:215], v[188:191], v[72:75]
	v_mfma_f32_16x16x32_bf16 v[68:71], v[204:207], v[196:199], v[68:71]
	v_mfma_f32_16x16x32_bf16 v[64:67], v[212:215], v[196:199], v[64:67]
	v_mfma_f32_16x16x32_bf16 v[104:107], v[208:211], v[176:179], v[104:107]
	v_mfma_f32_16x16x32_bf16 v[96:99], v[216:219], v[176:179], v[96:99]
	v_mfma_f32_16x16x32_bf16 v[88:91], v[208:211], v[184:187], v[88:91]
	v_mfma_f32_16x16x32_bf16 v[84:87], v[216:219], v[184:187], v[84:87]
	v_mfma_f32_16x16x32_bf16 v[76:79], v[208:211], v[192:195], v[76:79]
	v_mfma_f32_16x16x32_bf16 v[72:75], v[216:219], v[192:195], v[72:75]
	v_mfma_f32_16x16x32_bf16 v[68:71], v[208:211], v[200:203], v[68:71]
	v_mfma_f32_16x16x32_bf16 v[64:67], v[216:219], v[200:203], v[64:67]
	s_setprio 0
	s_mov_b32 m0, s58
	v_lshl_add_u64 v[220:221], v[224:225], 0, s[18:19]
	s_barrier
	ds_read_b128 v[162:165], v174 offset:49152
	ds_read_b128 v[176:179], v174 offset:50176
	ds_read_b128 v[180:183], v174 offset:51200
	ds_read_b128 v[184:187], v174 offset:52224
	ds_read_b128 v[188:191], v174 offset:53248
	ds_read_b128 v[192:195], v174 offset:54272
	ds_read_b128 v[196:199], v174 offset:55296
	ds_read_b128 v[200:203], v174 offset:56320
	global_load_lds_dwordx4 v[220:221], off
	v_lshl_add_u64 v[220:221], v[226:227], 0, s[18:19]
	s_mov_b32 m0, s59
	s_nop 0
	global_load_lds_dwordx4 v[220:221], off
	s_barrier
	s_waitcnt lgkmcnt(0)
	s_setprio 1
	s_waitcnt lgkmcnt(0)
	v_mfma_f32_16x16x32_bf16 v[60:63], v[128:131], v[162:165], v[60:63]
	v_mfma_f32_16x16x32_bf16 v[56:59], v[136:139], v[162:165], v[56:59]
	v_mfma_f32_16x16x32_bf16 v[48:51], v[128:131], v[180:183], v[48:51]
	v_mfma_f32_16x16x32_bf16 v[40:43], v[136:139], v[180:183], v[40:43]
	v_mfma_f32_16x16x32_bf16 v[32:35], v[128:131], v[188:191], v[32:35]
	v_mfma_f32_16x16x32_bf16 v[24:27], v[136:139], v[188:191], v[24:27]
	v_mfma_f32_16x16x32_bf16 v[16:19], v[128:131], v[196:199], v[16:19]
	v_mfma_f32_16x16x32_bf16 v[8:11], v[136:139], v[196:199], v[8:11]
	v_mfma_f32_16x16x32_bf16 v[60:63], v[132:135], v[176:179], v[60:63]
	v_mfma_f32_16x16x32_bf16 v[56:59], v[140:143], v[176:179], v[56:59]
	v_mfma_f32_16x16x32_bf16 v[48:51], v[132:135], v[184:187], v[48:51]
	v_mfma_f32_16x16x32_bf16 v[40:43], v[140:143], v[184:187], v[40:43]
	v_mfma_f32_16x16x32_bf16 v[32:35], v[132:135], v[192:195], v[32:35]
	v_mfma_f32_16x16x32_bf16 v[24:27], v[140:143], v[192:195], v[24:27]
	v_mfma_f32_16x16x32_bf16 v[16:19], v[132:135], v[200:203], v[16:19]
	v_mfma_f32_16x16x32_bf16 v[8:11], v[140:143], v[200:203], v[8:11]
	s_setprio 0
	s_barrier
	s_add_u32 s34, s34, 0x20080
	s_addc_u32 s35, s35, 0
	s_add_i32 s36, s36, s40
	v_lshl_add_u64 v[128:129], s[34:35], 0, v[150:151]
	s_mov_b32 m0, s36
	s_nop 0
	global_load_lds_dwordx4 v[128:129], off
	v_lshl_add_u64 v[128:129], s[34:35], 0, v[146:147]
	s_add_i32 m0, s36, 0x2000
	s_nop 0
	global_load_lds_dwordx4 v[128:129], off
	s_waitcnt vmcnt(6)
	s_barrier
; #define PG8_MMA(ai, bj, At, Bt) do { __builtin_amdgcn_s_setprio(1); _Pragma("unroll") for (int m = 0; m < 4; ++m) _Pragma("unroll") for (int n = 0; n < 2; ++n) _Pragma("unroll") for (int k = 0; k < 2; ++k) \
;         acc[ai][bj][m][n] = __builtin_amdgcn_mfma_f32_16x16x32_bf16(Bt[n][k], At[m][k], acc[ai][bj][m][n], 0, 0, 0); __builtin_amdgcn_s_setprio(0); } while (0)
; #define PG8_WAIT_V(n) asm volatile("s_waitcnt vmcnt(" #n ")" ::: "memory")
; #define PG8_BAR __builtin_amdgcn_s_barrier()
;     ...
;             PG8_WAIT_V(6); PG8_BAR; PG8_MMA(1, 1, At, B1); PG8_BAR;
;         }
;     __device__ __forceinline__ void operator()(const f32x4 (&acc)[2][2][4][2], const Unit& u, int wr, int wc, int fr, int fq) const {
;         const int row0 = u.pm * 256 + wr * 64 + fr, col0 = u.pn * 256 + wc * 32 + 8 * fq;
;         f32x4 bv[2][2];
; #pragma unroll
;         for (int bj = 0; bj < 2; ++bj)
; #pragma unroll
;             for (int n = 0; n < 2; ++n) bv[bj][n] = *(const f32x4*)(scale + col0 + bj * 128 + 4 * n);
; #pragma unroll
;         for (int ai = 0; ai < 2; ++ai)
; #pragma unroll
;             for (int m = 0; m < 4; ++m) {
;                 bf16_t* rowp = z + (size_t)(row0 + ai * 128 + m * 16) * DIN + O_U + col0;
	s_setprio 1
	v_mfma_f32_16x16x32_bf16 v[52:55], v[204:207], v[162:165], v[52:55]
	v_mfma_f32_16x16x32_bf16 v[44:47], v[212:215], v[162:165], v[44:47]
	v_mfma_f32_16x16x32_bf16 v[36:39], v[204:207], v[180:183], v[36:39]
	v_mfma_f32_16x16x32_bf16 v[28:31], v[212:215], v[180:183], v[28:31]
	v_mfma_f32_16x16x32_bf16 v[20:23], v[204:207], v[188:191], v[20:23]
	v_mfma_f32_16x16x32_bf16 v[12:15], v[212:215], v[188:191], v[12:15]
	v_mfma_f32_16x16x32_bf16 v[4:7], v[204:207], v[196:199], v[4:7]
	v_mfma_f32_16x16x32_bf16 v[0:3], v[212:215], v[196:199], v[0:3]
	v_mfma_f32_16x16x32_bf16 v[52:55], v[208:211], v[176:179], v[52:55]
	v_mfma_f32_16x16x32_bf16 v[44:47], v[216:219], v[176:179], v[44:47]
	v_mfma_f32_16x16x32_bf16 v[36:39], v[208:211], v[184:187], v[36:39]
	v_mfma_f32_16x16x32_bf16 v[28:31], v[216:219], v[184:187], v[28:31]
	v_mfma_f32_16x16x32_bf16 v[20:23], v[208:211], v[192:195], v[20:23]
	v_mfma_f32_16x16x32_bf16 v[12:15], v[216:219], v[192:195], v[12:15]
	v_mfma_f32_16x16x32_bf16 v[4:7], v[208:211], v[200:203], v[4:7]
	v_mfma_f32_16x16x32_bf16 v[0:3], v[216:219], v[200:203], v[0:3]
	s_setprio 0
	s_add_i32 s44, s44, 2
	s_add_u32 s42, s42, 0x100
	s_addc_u32 s43, s43, 0
	s_add_u32 s30, s30, 0x100
	s_addc_u32 s31, s31, 0
	s_cmp_gt_u32 s44, 1
	s_barrier
	s_cbranch_scc0 .LBB0_344
	v_lshl_or_b32 v164, s6, 8, v172
	v_ashrrev_i32_e32 v165, 31, v164
	v_lshl_add_u64 v[128:129], v[164:165], 2, s[16:17]
	global_load_dwordx4 v[140:143], v[128:129], off
	global_load_dwordx4 v[136:139], v[128:129], off offset:16
	global_load_dwordx4 v[132:135], v[128:129], off offset:512
	s_nop 0
	global_load_dwordx4 v[128:131], v[128:129], off offset:528
	v_lshl_add_u32 v188, s28, 8, v170
	v_mov_b64_e32 v[162:163], s[14:15]
	v_mad_i64_i32 v[176:177], s[6:7], v188, s64, v[162:163]
	v_lshlrev_b64 v[164:165], 1, v[164:165]
	v_or_b32_e32 v178, 16, v188
	v_lshl_add_u64 v[176:177], v[176:177], 0, v[164:165]
	v_mad_i64_i32 v[178:179], s[6:7], v178, s64, v[162:163]
	v_or_b32_e32 v180, 32, v188
	v_lshl_add_u64 v[178:179], v[178:179], 0, v[164:165]
	v_mad_i64_i32 v[180:181], s[6:7], v180, s64, v[162:163]
	v_or_b32_e32 v182, 48, v188
	v_lshl_add_u64 v[180:181], v[180:181], 0, v[164:165]
	v_mad_i64_i32 v[182:183], s[6:7], v182, s64, v[162:163]
	v_lshl_add_u64 v[182:183], v[182:183], 0, v[164:165]
	s_and_b64 vcc, exec, s[8:9]
	s_mov_b32 s28, s22
	s_mov_b64 s[30:31], s[26:27]
	s_mov_b64 s[34:35], s[24:25]
	s_waitcnt vmcnt(0)
; __device__ __forceinline__ u32x4 pack8(const f32x4 v0, const f32x4 v1) { u32x4 w; w.x = pk2(v0[0], v0[1]); w.y = pk2(v0[2], v0[3]); w.z = pk2(v1[0], v1[1]); w.w = pk2(v1[2], v1[3]); return w; }
;     __device__ __forceinline__ void operator()(const f32x4 (&acc)[2][2][4][2], const Unit& u, int wr, int wc, int fr, int fq) const {
;     ...
;         for (int ai = 0; ai < 2; ++ai)
; #pragma unroll
;             for (int m = 0; m < 4; ++m) {
;                 bf16_t* rowp = z + (size_t)(row0 + ai * 128 + m * 16) * DIN + O_U + col0;
; #pragma unroll
;                 for (int bj = 0; bj < 2; ++bj) *(u32x4*)(rowp + bj * 128) = pack8(acc[ai][bj][m][0] * bv[bj][0], acc[ai][bj][m][1] * bv[bj][1]);
;             }
	v_pk_mul_f32 v[124:125], v[124:125], v[140:141]
	v_pk_mul_f32 v[126:127], v[126:127], v[142:143]
	v_pk_mul_f32 v[122:123], v[122:123], v[138:139]
	v_pk_mul_f32 v[186:187], v[64:65], v[128:129]
	v_cvt_pk_bf16_f32 v64, v124, v125
	v_pk_mul_f32 v[120:121], v[120:121], v[136:137]
	v_pk_mul_f32 v[104:105], v[104:105], v[132:133]
	v_pk_mul_f32 v[184:185], v[66:67], v[130:131]
	v_cvt_pk_bf16_f32 v65, v126, v127
	v_cvt_pk_bf16_f32 v66, v120, v121
	v_cvt_pk_bf16_f32 v67, v122, v123
	global_store_dwordx4 v[176:177], v[64:67], off offset:3584 sc1
	v_pk_mul_f32 v[106:107], v[106:107], v[134:135]
	v_pk_mul_f32 v[98:99], v[98:99], v[130:131]
	v_cvt_pk_bf16_f32 v64, v104, v105
	v_pk_mul_f32 v[96:97], v[96:97], v[128:129]
	v_pk_mul_f32 v[116:117], v[116:117], v[140:141]
	v_cvt_pk_bf16_f32 v65, v106, v107
	v_cvt_pk_bf16_f32 v66, v96, v97
	v_cvt_pk_bf16_f32 v67, v98, v99
	global_store_dwordx4 v[176:177], v[64:67], off offset:3840 sc1
	v_pk_mul_f32 v[118:119], v[118:119], v[142:143]
	v_pk_mul_f32 v[114:115], v[114:115], v[138:139]
	v_cvt_pk_bf16_f32 v64, v116, v117
	v_pk_mul_f32 v[112:113], v[112:113], v[136:137]
	v_pk_mul_f32 v[88:89], v[88:89], v[132:133]
	v_cvt_pk_bf16_f32 v65, v118, v119
	v_cvt_pk_bf16_f32 v66, v112, v113
	v_cvt_pk_bf16_f32 v67, v114, v115
	global_store_dwordx4 v[178:179], v[64:67], off offset:3584 sc1
	v_pk_mul_f32 v[90:91], v[90:91], v[134:135]
	v_pk_mul_f32 v[86:87], v[86:87], v[130:131]
	v_cvt_pk_bf16_f32 v64, v88, v89
	v_pk_mul_f32 v[84:85], v[84:85], v[128:129]
	v_pk_mul_f32 v[108:109], v[108:109], v[140:141]
	v_cvt_pk_bf16_f32 v65, v90, v91
	v_cvt_pk_bf16_f32 v66, v84, v85
	v_cvt_pk_bf16_f32 v67, v86, v87
	global_store_dwordx4 v[178:179], v[64:67], off offset:3840 sc1
	v_pk_mul_f32 v[110:111], v[110:111], v[142:143]
	v_pk_mul_f32 v[102:103], v[102:103], v[138:139]
	v_cvt_pk_bf16_f32 v64, v108, v109
	v_pk_mul_f32 v[100:101], v[100:101], v[136:137]
	v_pk_mul_f32 v[76:77], v[76:77], v[132:133]
	v_cvt_pk_bf16_f32 v65, v110, v111
	v_cvt_pk_bf16_f32 v66, v100, v101
	v_cvt_pk_bf16_f32 v67, v102, v103
	global_store_dwordx4 v[180:181], v[64:67], off offset:3584 sc1
	v_pk_mul_f32 v[78:79], v[78:79], v[134:135]
	v_pk_mul_f32 v[74:75], v[74:75], v[130:131]
	v_cvt_pk_bf16_f32 v64, v76, v77
	v_pk_mul_f32 v[72:73], v[72:73], v[128:129]
	v_pk_mul_f32 v[92:93], v[92:93], v[140:141]
	v_cvt_pk_bf16_f32 v65, v78, v79
	v_cvt_pk_bf16_f32 v66, v72, v73
	v_cvt_pk_bf16_f32 v67, v74, v75
	global_store_dwordx4 v[180:181], v[64:67], off offset:3840 sc1
	v_pk_mul_f32 v[94:95], v[94:95], v[142:143]
	v_pk_mul_f32 v[82:83], v[82:83], v[138:139]
	v_cvt_pk_bf16_f32 v64, v92, v93
	v_pk_mul_f32 v[80:81], v[80:81], v[136:137]
	v_pk_mul_f32 v[68:69], v[68:69], v[132:133]
	v_cvt_pk_bf16_f32 v65, v94, v95
	v_cvt_pk_bf16_f32 v66, v80, v81
	v_cvt_pk_bf16_f32 v67, v82, v83
	global_store_dwordx4 v[182:183], v[64:67], off offset:3584 sc1
	v_pk_mul_f32 v[70:71], v[70:71], v[134:135]
	v_pk_mul_f32 v[62:63], v[62:63], v[142:143]
	v_cvt_pk_bf16_f32 v64, v68, v69
	v_cvt_pk_bf16_f32 v65, v70, v71
	v_cvt_pk_bf16_f32 v66, v186, v187
	v_cvt_pk_bf16_f32 v67, v184, v185
	global_store_dwordx4 v[182:183], v[64:67], off offset:3840 sc1
	v_pk_mul_f32 v[60:61], v[60:61], v[140:141]
	v_pk_mul_f32 v[52:53], v[52:53], v[132:133]
	v_add_u32_e32 v64, 0x80, v188
	v_mad_i64_i32 v[64:65], s[6:7], v64, s64, v[162:163]
	v_lshl_add_u64 v[64:65], v[64:65], 0, v[164:165]
	v_pk_mul_f32 v[66:67], v[58:59], v[138:139]
	v_pk_mul_f32 v[58:59], v[56:57], v[136:137]
	v_cvt_pk_bf16_f32 v56, v60, v61
	v_cvt_pk_bf16_f32 v57, v62, v63
	v_pk_mul_f32 v[54:55], v[54:55], v[134:135]
	v_cvt_pk_bf16_f32 v58, v58, v59
	v_cvt_pk_bf16_f32 v59, v66, v67
	global_store_dwordx4 v[64:65], v[56:59], off offset:3584 sc1
	v_pk_mul_f32 v[48:49], v[48:49], v[140:141]
	v_pk_mul_f32 v[36:37], v[36:37], v[132:133]
	v_pk_mul_f32 v[56:57], v[46:47], v[130:131]
	v_pk_mul_f32 v[46:47], v[44:45], v[128:129]
	v_cvt_pk_bf16_f32 v44, v52, v53
	v_cvt_pk_bf16_f32 v45, v54, v55
	v_pk_mul_f32 v[38:39], v[38:39], v[134:135]
	v_cvt_pk_bf16_f32 v46, v46, v47
	v_cvt_pk_bf16_f32 v47, v56, v57
	global_store_dwordx4 v[64:65], v[44:47], off offset:3840 sc1
	v_pk_mul_f32 v[32:33], v[32:33], v[140:141]
	v_pk_mul_f32 v[20:21], v[20:21], v[132:133]
	v_add_u32_e32 v44, 0x90, v188
	v_mad_i64_i32 v[44:45], s[6:7], v44, s64, v[162:163]
	v_lshl_add_u64 v[44:45], v[44:45], 0, v[164:165]
	v_pk_mul_f32 v[46:47], v[50:51], v[142:143]
	v_pk_mul_f32 v[50:51], v[42:43], v[138:139]
	v_pk_mul_f32 v[42:43], v[40:41], v[136:137]
	v_cvt_pk_bf16_f32 v40, v48, v49
	v_cvt_pk_bf16_f32 v41, v46, v47
	v_pk_mul_f32 v[22:23], v[22:23], v[134:135]
	v_cvt_pk_bf16_f32 v42, v42, v43
	v_cvt_pk_bf16_f32 v43, v50, v51
	global_store_dwordx4 v[44:45], v[40:43], off offset:3584 sc1
	v_pk_mul_f32 v[16:17], v[16:17], v[140:141]
	v_pk_mul_f32 v[6:7], v[6:7], v[134:135]
	v_pk_mul_f32 v[40:41], v[30:31], v[130:131]
	v_pk_mul_f32 v[30:31], v[28:29], v[128:129]
	v_cvt_pk_bf16_f32 v28, v36, v37
	v_cvt_pk_bf16_f32 v29, v38, v39
	v_pk_mul_f32 v[4:5], v[4:5], v[132:133]
	v_cvt_pk_bf16_f32 v30, v30, v31
	v_cvt_pk_bf16_f32 v31, v40, v41
	global_store_dwordx4 v[44:45], v[28:31], off offset:3840 sc1
	s_nop 1
	v_add_u32_e32 v28, 0xa0, v188
	v_mad_i64_i32 v[28:29], s[6:7], v28, s64, v[162:163]
	v_lshl_add_u64 v[28:29], v[28:29], 0, v[164:165]
	v_pk_mul_f32 v[30:31], v[34:35], v[142:143]
	v_pk_mul_f32 v[34:35], v[26:27], v[138:139]
	v_pk_mul_f32 v[26:27], v[24:25], v[136:137]
	v_cvt_pk_bf16_f32 v24, v32, v33
	v_cvt_pk_bf16_f32 v25, v30, v31
	s_nop 0
	v_cvt_pk_bf16_f32 v26, v26, v27
	v_cvt_pk_bf16_f32 v27, v34, v35
	global_store_dwordx4 v[28:29], v[24:27], off offset:3584 sc1
	s_nop 1
	v_pk_mul_f32 v[24:25], v[14:15], v[130:131]
	v_pk_mul_f32 v[14:15], v[12:13], v[128:129]
	v_cvt_pk_bf16_f32 v12, v20, v21
	v_cvt_pk_bf16_f32 v13, v22, v23
	s_nop 0
	v_cvt_pk_bf16_f32 v14, v14, v15
	v_cvt_pk_bf16_f32 v15, v24, v25
	global_store_dwordx4 v[28:29], v[12:15], off offset:3840 sc1
	s_nop 1
	v_add_u32_e32 v12, 0xb0, v188
	v_mad_i64_i32 v[12:13], s[6:7], v12, s64, v[162:163]
	v_lshl_add_u64 v[12:13], v[12:13], 0, v[164:165]
	v_pk_mul_f32 v[14:15], v[18:19], v[142:143]
	v_pk_mul_f32 v[18:19], v[10:11], v[138:139]
	v_pk_mul_f32 v[10:11], v[8:9], v[136:137]
	v_cvt_pk_bf16_f32 v8, v16, v17
	v_cvt_pk_bf16_f32 v9, v14, v15
	s_mov_b32 s6, s20
	v_cvt_pk_bf16_f32 v10, v10, v11
	v_cvt_pk_bf16_f32 v11, v18, v19
	global_store_dwordx4 v[12:13], v[8:11], off offset:3584 sc1
	s_nop 1
	v_pk_mul_f32 v[8:9], v[2:3], v[130:131]
	v_pk_mul_f32 v[2:3], v[0:1], v[128:129]
	v_cvt_pk_bf16_f32 v0, v4, v5
	v_cvt_pk_bf16_f32 v1, v6, v7
	s_nop 0
	v_cvt_pk_bf16_f32 v2, v2, v3
	v_cvt_pk_bf16_f32 v3, v8, v9
	global_store_dwordx4 v[12:13], v[0:3], off offset:3840 sc1
	s_cbranch_vccz .LBB0_341
	s_waitcnt vmcnt(0)
	s_cmpk_gt_u32 s39, 0xff
	s_cbranch_scc1 .LBB0_348
	s_barrier

; #define PG8_STAGE(bufoff, gbase, voff) do { _Pragma("unroll") for (int _i = 0; _i < 2; ++_i) \
;         __builtin_amdgcn_global_load_lds((const unsigned*)((const char*)(gbase) + (voff)[_i]), (LAS unsigned*)(lds + (bufoff) + ldsw + _i * 8192), 16, 0, 0); } while (0)
; #define PG8_WAIT_V(n) asm volatile("s_waitcnt vmcnt(" #n ")" ::: "memory")
; #define PG8_BAR __builtin_amdgcn_s_barrier()
;     __device__ bool next(int i, Unit& u) const {
;         const long L = (long)i * G + c; if (L >= nwg) return false;
;         int wgid = (int)L; { const int q = nwg / NXCD, r = nwg % NXCD, xcd = wgid % NXCD, off = wgid / NXCD; wgid = (xcd < r ? xcd * (q + 1) : r * (q + 1) + (xcd - r) * q) + off; }
;         const int nig = WGM * nN, gid = wgid / nig, fm = gid * WGM, gsz = (nM - fm) < WGM ? (nM - fm) : WGM;
;         u.pm = fm + ((wgid % nig) % gsz); u.pn = (wgid % nig) / gsz; return true;
;     ...
;     for (int i = 0; i < 2; ++i) { int R, C; stage_rc(tid * 16 + i * 8192, R, C); const int Rb = Epi::PERM ? ((R & ~31) + perm32(R & 31)) : R;
;         voffA[i] = (unsigned)(R * lda + C) * 2u; voffB[i] = (unsigned)(Rb * ldb + C) * 2u; }
;     const size_t kstep = (size_t)(BK * 2);
;     const size_t hA = (size_t)HALF * lda * 2, hB = (size_t)HALF * ldb * 2;
;     const size_t tA = 2 * hA, tB = 2 * hB;
;     const unsigned ldsw = (unsigned)wid * 1024u;
;     const int aoff = lds_byte(wr * 64 + fr, fq * 8), boff = lds_byte(wc * 32 + fr, fq * 8);
;     ...
;     Unit cur, nxt; int ui = 0;
;     if (!S.next(0, cur)) return;
;     ...
;     f32x4 acc[2][2][4][2];
; #pragma unroll
;     for (int a = 0; a < 2; ++a)
; #pragma unroll
;         for (int b = 0; b < 2; ++b)
; #pragma unroll
;             for (int m = 0; m < 4; ++m)
; #pragma unroll
;                 for (int n = 0; n < 2; ++n) acc[a][b][m][n] = (f32x4){0.f, 0.f, 0.f, 0.f};
;     bf16x8 At[4][2], B0[2][2], B1[2][2];
;     const char* cA = (const char*)g.A + (size_t)cur.pm * tA; const char* cB = (const char*)g.Bt + (size_t)cur.pn * tB;
;     PG8_A_READY(cur);
;     PG8_STAGE(PG8_SB(0, 0), cB, voffB); PG8_STAGE(PG8_SA(0, 0), cA, voffA); PG8_STAGE(PG8_SB(0, 1), cB + hB, voffB); PG8_STAGE(PG8_SA(0, 1), cA + hA, voffA);
;     if (wr == 1) PG8_BAR;
;     PG8_WAIT_V(4); PG8_BAR;
;     PG8_STAGE(PG8_SB(1, 0), cB + kstep, voffB); PG8_STAGE(PG8_SA(1, 0), cA + kstep, voffA); PG8_STAGE(PG8_SB(1, 1), cB + hB + kstep, voffB);
.LBB0_1478:
	s_abs_i32 s6, s53
	s_waitcnt vmcnt(0)
	v_cvt_f32_u32_e32 v0, s6
	s_sub_i32 s9, 0, s6
	s_add_i32 s7, s68, 0x88
	s_ashr_i32 s8, s7, 31
	v_rcp_iflag_f32_e32 v0, v0
	s_abs_i32 s7, s7
	s_load_dwordx2 s[12:13], s[0:1], 0x120
	s_waitcnt lgkmcnt(0)
	s_load_dwordx2 s[14:15], s[0:1], 0xf0
	s_waitcnt lgkmcnt(0)
	v_mul_f32_e32 v0, 0x4f7ffffe, v0
	v_cvt_u32_f32_e32 v0, v0
	s_load_dwordx2 s[16:17], s[0:1], 0x130
	s_waitcnt lgkmcnt(0)
	s_load_dwordx2 s[18:19], s[0:1], 0xa0
	s_waitcnt lgkmcnt(0)
	v_mov_b32_e32 v8, v166
	v_readfirstlane_b32 s10, v0
	s_mul_i32 s9, s9, s10
	s_mul_hi_u32 s9, s10, s9
	s_add_i32 s10, s10, s9
	s_mul_hi_u32 s9, s7, s10
	s_mul_i32 s9, s9, s6
	s_sub_i32 s7, s7, s9
	s_sub_i32 s9, s7, s6
	s_cmp_ge_u32 s7, s6
	s_cselect_b32 s7, s9, s7
	s_sub_i32 s9, s7, s6
	s_cmp_ge_u32 s7, s6
	s_cselect_b32 s6, s9, s7
	s_xor_b32 s6, s6, s8
	s_sub_i32 s40, s6, s8
	s_cmpk_gt_i32 s40, 0x87
	v_readfirstlane_b32 s41, v8
	s_cbranch_scc1 .LBB0_1490
	v_lshlrev_b32_e32 v0, 4, v8
	v_add_u32_e32 v1, 0x2000, v0
	v_ashrrev_i32_e32 v2, 31, v1
	v_lshrrev_b32_e32 v2, 22, v2
	v_add_u32_e32 v2, v1, v2
	v_ashrrev_i32_e32 v9, 10, v2
	v_mul_i32_i24_e32 v2, 0x400, v9
	v_sub_u32_e32 v1, v1, v2
	v_lshrrev_b32_e32 v2, 4, v1
	v_bitop3_b32 v1, v2, v1, 32 bitop3:0x6c
	v_ashrrev_i32_e32 v2, 31, v1
	v_lshrrev_b32_e32 v2, 26, v2
	v_add_u32_e32 v2, v1, v2
	v_lshlrev_b32_e32 v3, 3, v9
	v_ashrrev_i32_e32 v10, 6, v2
	v_and_b32_e32 v3, -16, v3
	v_add_u32_e32 v3, v10, v3
	v_and_b32_e32 v4, 3, v10
	s_mov_b32 s8, 0x3fffe0
	v_lshrrev_b32_e32 v5, 2, v3
	v_lshlrev_b32_e32 v6, 1, v3
	v_and_b32_e32 v2, 0xc0, v2
	v_and_or_b32 v4, v3, s8, v4
	v_and_b32_e32 v5, 4, v5
	v_and_b32_e32 v6, 24, v6
	v_sub_u32_e32 v1, v1, v2
	v_mov_b32_e32 v2, 1
	v_or3_b32 v4, v4, v5, v6
	v_lshlrev_b32_e32 v5, 5, v9
	v_ashrrev_i16_sdwa v1, v2, sext(v1) dst_sel:DWORD dst_unused:UNUSED_PAD src0_sel:DWORD src1_sel:BYTE_0
	v_and_b32_e32 v5, 32, v5
	v_bfe_i32 v11, v1, 0, 16
	v_add_lshl_u32 v1, v5, v11, 1
	v_lshl_add_u32 v146, v4, 10, v1
	v_lshl_add_u32 v148, v3, 10, v1
	v_bfe_i32 v1, v8, 27, 1
	v_lshrrev_b32_e32 v1, 22, v1
	v_add_u32_e32 v1, v0, v1
	v_and_b32_e32 v1, 0xfffffc00, v1
	v_sub_u32_e32 v0, v0, v1
	v_lshrrev_b32_e32 v1, 4, v0
	v_ashrrev_i32_e32 v3, 31, v8
	v_bitop3_b32 v0, v1, v0, 32 bitop3:0x6c
	v_lshrrev_b32_e32 v3, 26, v3
	v_ashrrev_i32_e32 v1, 31, v0
	v_add_u32_e32 v3, v8, v3
	v_lshrrev_b32_e32 v1, 26, v1
	v_ashrrev_i32_e32 v13, 6, v3
	v_add_u32_e32 v1, v0, v1
	v_lshlrev_b32_e32 v3, 3, v13
	v_ashrrev_i32_e32 v12, 6, v1
	v_and_b32_e32 v3, -16, v3
	v_add_u32_e32 v3, v12, v3
	v_and_b32_e32 v4, 3, v12
	s_ashr_i32 s43, s40, 31
	v_and_or_b32 v4, v3, s8, v4
	s_lshr_b32 s8, s43, 29
	s_add_i32 s8, s40, s8
	s_ashr_i32 s6, s41, 6
	s_ashr_i32 s9, s8, 3
	s_and_b32 s8, s8, -8
	s_ashr_i32 s7, s41, 8
	s_lshl_b32 s42, s6, 10
	s_sub_i32 s8, s40, s8
	s_cmp_lt_i32 s8, 0
	s_cselect_b32 s10, 18, 17
	s_mul_i32 s8, s10, s8
	s_add_i32 s8, s8, s9
	s_ashr_i32 s9, s8, 31
	s_lshr_b32 s9, s9, 28
	s_add_i32 s9, s8, s9
	v_lshrrev_b32_e32 v5, 2, v3
	v_lshlrev_b32_e32 v6, 1, v3
	v_and_b32_e32 v1, 0xc0, v1
	s_ashr_i32 s10, s9, 4
	v_and_b32_e32 v5, 4, v5
	v_and_b32_e32 v6, 24, v6
	v_sub_u32_e32 v0, v0, v1
	s_lshl_b32 s11, s10, 3
	v_or3_b32 v4, v4, v5, v6
	v_lshlrev_b32_e32 v5, 5, v13
	v_ashrrev_i16_sdwa v0, v2, sext(v0) dst_sel:DWORD dst_unused:UNUSED_PAD src0_sel:DWORD src1_sel:BYTE_0
	s_sub_i32 s10, 0x44, s11
	v_and_b32_e32 v5, 32, v5
	v_bfe_i32 v14, v0, 0, 16
	s_min_u32 s20, s10, 8
	s_and_b32 s9, s9, -16
	v_add_lshl_u32 v0, v5, v14, 1
	s_sub_i32 s21, s8, s9
	v_cvt_f32_ubyte0_e32 v2, s20
	v_lshl_add_u32 v150, v4, 10, v0
	v_cvt_f32_i32_e32 v1, s21
	v_rcp_iflag_f32_e32 v4, v2
	v_lshl_add_u32 v152, v3, 10, v0
	s_ashr_i32 s8, s21, 30
	s_or_b32 s10, s8, 1
	v_mul_f32_e32 v0, v1, v4
	v_trunc_f32_e32 v0, v0
	v_fma_f32 v1, -v0, v2, v1
	v_cvt_i32_f32_e32 v0, v0
	v_cmp_ge_f32_e64 s[8:9], |v1|, v2
	s_and_b64 s[8:9], s[8:9], exec
	s_cselect_b32 s8, s10, 0
	v_readfirstlane_b32 s9, v0
	s_add_i32 s10, s9, s8
	s_mul_i32 s8, s10, s20
	s_sub_i32 s8, s21, s8
	s_sext_i32_i8 s8, s8
	s_add_i32 s30, s11, s8
	s_ashr_i32 s31, s30, 31
	s_bfe_i64 s[20:21], s[10:11], 0x80000
	s_lshl_b64 s[8:9], s[30:31], 18
	s_lshl_b64 s[20:21], s[20:21], 18
	s_lshr_b32 s98, s20, 9
	s_add_u32 s20, s20, s98
	s_add_u32 s8, s8, s98
	s_add_u32 s34, s14, s20
	s_addc_u32 s35, s15, s21
	s_add_i32 s31, s42, 0
	s_add_i32 m0, s31, 0x10000
	v_mov_b32_e32 v151, 0
	global_load_lds_dwordx4 v150, s[34:35]
	s_add_i32 m0, s31, 0x12000
	s_add_u32 s36, s12, s8
	global_load_lds_dwordx4 v146, s[34:35]
	s_addc_u32 s37, s13, s9
	s_mov_b32 m0, s31
	s_add_i32 s54, s31, 0x2000
	global_load_lds_dwordx4 v152, s[36:37]
	s_mov_b32 m0, s54
	s_add_u32 s8, s34, 0x20000
	global_load_lds_dwordx4 v148, s[36:37]
	s_addc_u32 s9, s35, 0
	s_add_i32 m0, s31, 0x14000
	v_mov_b32_e32 v147, v151
	global_load_lds_dwordx4 v150, s[8:9]
	s_add_i32 m0, s31, 0x16000
	v_mov_b32_e32 v153, v151
	global_load_lds_dwordx4 v146, s[8:9]
	s_add_u32 s8, s36, 0x20000
	s_addc_u32 s9, s37, 0
	s_add_i32 s55, s31, 0x4000
	s_mov_b32 m0, s55
	s_add_i32 s56, s31, 0x6000
	global_load_lds_dwordx4 v152, s[8:9]
	s_mov_b32 m0, s56
	v_mov_b32_e32 v149, v151
	global_load_lds_dwordx4 v148, s[8:9]
	v_lshl_add_u64 v[6:7], s[34:35], 0, v[150:151]
	v_lshl_add_u64 v[4:5], s[34:35], 0, v[146:147]
	v_lshl_add_u64 v[2:3], s[36:37], 0, v[152:153]
	s_cmp_lg_u32 s7, 1
	v_lshl_add_u64 v[0:1], s[36:37], 0, v[148:149]
	s_cbranch_scc1 .LBB0_1481
	s_barrier

; #define PG8_WAIT_V(n) asm volatile("s_waitcnt vmcnt(" #n ")" ::: "memory")
;     ...
;         const bool has_next = S.next(ui + 1, nxt);
;         const char* nA = has_next ? (const char*)g.A + (size_t)nxt.pm * tA : cA; const char* nB = has_next ? (const char*)g.Bt + (size_t)nxt.pn * tB : cB;
; #pragma unroll 1
;         for (int t = 0; t < nt; t += 2) {
;             const bool last = (t == nt - 2);
;             const char* a1 = cA + (size_t)(t + 1) * kstep;
;             const char* a2 = last ? nA : cA + (size_t)(t + 2) * kstep; const char* b2 = last ? nB : cB + (size_t)(t + 2) * kstep;
;             const char* a3 = a2 + kstep; const char* b3 = b2 + kstep;
;             if (last && has_next) PG8_A_READY(nxt);
;             PG8_LDB(B0, 0, 0); PG8_SCHED; PG8_LDA(At, 0, 0); PG8_STAGE(PG8_SA(1, 1), a1 + hA, voffA);
;             PG8_WAIT_L(8); PG8_BAR; PG8_WAIT_L(0); PG8_MMA(0, 0, At, B0); PG8_BAR; PG8_SCHED;
;             PG8_LDB(B1, 0, 1); PG8_STAGE(PG8_SB(0, 0), b2, voffB);
;             PG8_BAR; PG8_WAIT_L(0); PG8_MMA(0, 1, At, B1); PG8_BAR;
;             PG8_LDA(At, 0, 1); PG8_STAGE(PG8_SA(0, 0), a2, voffA);
;             PG8_BAR; PG8_WAIT_L(0); PG8_MMA(1, 0, At, B0); PG8_BAR; PG8_SCHED;
;             PG8_STAGE(PG8_SB(0, 1), b2 + hB, voffB);
;             PG8_WAIT_V(6); PG8_BAR; PG8_MMA(1, 1, At, B1); PG8_BAR;
;             PG8_LDB(B0, 1, 0); PG8_SCHED; PG8_LDA(At, 1, 0); PG8_STAGE(PG8_SA(0, 1), a2 + hA, voffA);
;             PG8_WAIT_L(8); PG8_BAR; PG8_WAIT_L(0); PG8_MMA(0, 0, At, B0); PG8_BAR; PG8_SCHED;
;             PG8_LDB(B1, 1, 1); PG8_STAGE(PG8_SB(1, 0), b3, voffB);
;             PG8_BAR; PG8_WAIT_L(0); PG8_MMA(0, 1, At, B1); PG8_BAR;
;             PG8_LDA(At, 1, 1); PG8_STAGE(PG8_SA(1, 0), a3, voffA);
;             PG8_BAR; PG8_WAIT_L(0); PG8_MMA(1, 0, At, B0); PG8_BAR; PG8_SCHED;
;             PG8_STAGE(PG8_SB(1, 1), b3 + hB, voffB);
;             PG8_WAIT_V(6); PG8_BAR; PG8_MMA(1, 1, At, B1); PG8_BAR;
;         }
;         E(acc, cur, wr, wc, fr, fq);
;         if (!has_next) break;
; #pragma unroll
;         for (int a = 0; a < 2; ++a)
; #pragma unroll
;             for (int b = 0; b < 2; ++b)
; #pragma unroll
;                 for (int m = 0; m < 4; ++m)
; #pragma unroll
;                     for (int n = 0; n < 2; ++n) acc[a][b][m][n] = (f32x4){0.f, 0.f, 0.f, 0.f};
;         cur = nxt; cA = nA; cB = nB; ++ui;
.LBB0_1484:
	s_ashr_i32 s25, s24, 31
	s_lshl_b64 s[8:9], s[24:25], 18
	s_lshl_b32 s98, s22, 9
	s_add_u32 s8, s8, s98
	v_cmp_lt_i64_e32 vcc, s[26:27], v[158:159]
	s_add_u32 s26, s12, s8
	s_addc_u32 s27, s13, s9
	s_and_b64 s[8:9], vcc, exec
	s_cselect_b32 s7, s27, s37
	s_cselect_b32 s8, s26, s36
	s_ashr_i32 s23, s22, 31
	s_lshl_b64 s[28:29], s[22:23], 18
	s_add_u32 s28, s28, s98
	s_add_u32 s28, s14, s28
	s_addc_u32 s29, s15, s29
	s_and_b64 s[38:39], vcc, exec
	s_cselect_b32 s9, s29, s35
	s_cselect_b32 s23, s28, s34
	s_add_u32 s25, s34, 0x100
	s_addc_u32 s33, s35, 0
	s_add_u32 s34, s36, 0x20080
	v_mov_b32_e32 v0, 0
	s_addc_u32 s35, s37, 0
	s_mov_b32 s44, -2
	v_mov_b32_e32 v1, v0
	v_mov_b32_e32 v2, v0
	v_mov_b32_e32 v3, v0
	v_mov_b32_e32 v4, v0
	v_mov_b32_e32 v5, v0
	v_mov_b32_e32 v6, v0
	v_mov_b32_e32 v7, v0
	v_mov_b32_e32 v12, v0
	v_mov_b32_e32 v13, v0
	v_mov_b32_e32 v14, v0
	v_mov_b32_e32 v15, v0
	v_mov_b32_e32 v20, v0
	v_mov_b32_e32 v21, v0
	v_mov_b32_e32 v22, v0
	v_mov_b32_e32 v23, v0
	v_mov_b32_e32 v28, v0
	v_mov_b32_e32 v29, v0
	v_mov_b32_e32 v30, v0
	v_mov_b32_e32 v31, v0
	v_mov_b32_e32 v36, v0
	v_mov_b32_e32 v37, v0
	v_mov_b32_e32 v38, v0
	v_mov_b32_e32 v39, v0
	v_mov_b32_e32 v44, v0
	v_mov_b32_e32 v45, v0
	v_mov_b32_e32 v46, v0
	v_mov_b32_e32 v47, v0
	v_mov_b32_e32 v52, v0
	v_mov_b32_e32 v53, v0
	v_mov_b32_e32 v54, v0
	v_mov_b32_e32 v55, v0
	v_mov_b32_e32 v8, v0
	v_mov_b32_e32 v9, v0
	v_mov_b32_e32 v10, v0
	v_mov_b32_e32 v11, v0
	v_mov_b32_e32 v16, v0
	v_mov_b32_e32 v17, v0
	v_mov_b32_e32 v18, v0
	v_mov_b32_e32 v19, v0
	v_mov_b32_e32 v24, v0
	v_mov_b32_e32 v25, v0
	v_mov_b32_e32 v26, v0
	v_mov_b32_e32 v27, v0
	v_mov_b32_e32 v32, v0
	v_mov_b32_e32 v33, v0
	v_mov_b32_e32 v34, v0
	v_mov_b32_e32 v35, v0
	v_mov_b32_e32 v40, v0
	v_mov_b32_e32 v41, v0
	v_mov_b32_e32 v42, v0
	v_mov_b32_e32 v43, v0
	v_mov_b32_e32 v48, v0
	v_mov_b32_e32 v49, v0
	v_mov_b32_e32 v50, v0
	v_mov_b32_e32 v51, v0
	v_mov_b32_e32 v56, v0
	v_mov_b32_e32 v57, v0
	v_mov_b32_e32 v58, v0
	v_mov_b32_e32 v59, v0
	v_mov_b32_e32 v60, v0
	v_mov_b32_e32 v61, v0
	v_mov_b32_e32 v62, v0
	v_mov_b32_e32 v63, v0
	v_mov_b32_e32 v64, v0
	v_mov_b32_e32 v65, v0
	v_mov_b32_e32 v66, v0
	v_mov_b32_e32 v67, v0
	v_mov_b32_e32 v68, v0
	v_mov_b32_e32 v69, v0
	v_mov_b32_e32 v70, v0
	v_mov_b32_e32 v71, v0
	v_mov_b32_e32 v72, v0
	v_mov_b32_e32 v73, v0
	v_mov_b32_e32 v74, v0
	v_mov_b32_e32 v75, v0
	v_mov_b32_e32 v76, v0
	v_mov_b32_e32 v77, v0
	v_mov_b32_e32 v78, v0
	v_mov_b32_e32 v79, v0
	v_mov_b32_e32 v84, v0
	v_mov_b32_e32 v85, v0
	v_mov_b32_e32 v86, v0
	v_mov_b32_e32 v87, v0
	v_mov_b32_e32 v88, v0
	v_mov_b32_e32 v89, v0
	v_mov_b32_e32 v90, v0
	v_mov_b32_e32 v91, v0
	v_mov_b32_e32 v96, v0
	v_mov_b32_e32 v97, v0
	v_mov_b32_e32 v98, v0
	v_mov_b32_e32 v99, v0
	v_mov_b32_e32 v104, v0
	v_mov_b32_e32 v105, v0
	v_mov_b32_e32 v106, v0
	v_mov_b32_e32 v107, v0
	v_mov_b32_e32 v80, v0
	v_mov_b32_e32 v81, v0
	v_mov_b32_e32 v82, v0
	v_mov_b32_e32 v83, v0
	v_mov_b32_e32 v92, v0
	v_mov_b32_e32 v93, v0
	v_mov_b32_e32 v94, v0
	v_mov_b32_e32 v95, v0
	v_mov_b32_e32 v100, v0
	v_mov_b32_e32 v101, v0
	v_mov_b32_e32 v102, v0
	v_mov_b32_e32 v103, v0
	v_mov_b32_e32 v108, v0
	v_mov_b32_e32 v109, v0
	v_mov_b32_e32 v110, v0
	v_mov_b32_e32 v111, v0
	v_mov_b32_e32 v112, v0
	v_mov_b32_e32 v113, v0
	v_mov_b32_e32 v114, v0
	v_mov_b32_e32 v115, v0
	v_mov_b32_e32 v116, v0
	v_mov_b32_e32 v117, v0
	v_mov_b32_e32 v118, v0
	v_mov_b32_e32 v119, v0
	v_mov_b32_e32 v120, v0
	v_mov_b32_e32 v121, v0
	v_mov_b32_e32 v122, v0
	v_mov_b32_e32 v123, v0
	v_mov_b32_e32 v124, v0
	v_mov_b32_e32 v125, v0
	v_mov_b32_e32 v126, v0
	v_mov_b32_e32 v127, v0
.LBB0_1485:
	ds_read_b128 v[128:131], v172
	ds_read_b128 v[132:135], v172 offset:1024
	ds_read_b128 v[136:139], v172 offset:2048
	ds_read_b128 v[140:143], v172 offset:3072
	s_add_u32 s36, s34, 0xfffe0080
	s_addc_u32 s37, s35, -1
	s_cmp_eq_u32 s44, 0
	s_cselect_b32 s39, s7, s37
	s_cselect_b32 s38, s8, s36
	s_cselect_b32 s37, s9, s33
	s_cselect_b32 s36, s23, s25
	v_lshl_add_u64 v[204:205], s[34:35], 0, v[156:157]
	s_add_i32 m0, s31, 0xc000
	ds_read_b128 v[162:165], v173
	ds_read_b128 v[176:179], v173 offset:1024
	ds_read_b128 v[180:183], v173 offset:2048
	ds_read_b128 v[184:187], v173 offset:3072
	ds_read_b128 v[188:191], v173 offset:4096
	ds_read_b128 v[192:195], v173 offset:5120
	ds_read_b128 v[196:199], v173 offset:6144
	ds_read_b128 v[200:203], v173 offset:7168
	global_load_lds_dwordx4 v[204:205], off
	v_lshl_add_u64 v[204:205], s[34:35], 0, v[154:155]
	s_add_i32 m0, s31, 0xe000
	s_nop 0
	global_load_lds_dwordx4 v[204:205], off
	s_waitcnt lgkmcnt(8)
	s_barrier
	s_waitcnt lgkmcnt(0)
	s_setprio 1
	s_waitcnt lgkmcnt(0)
	v_mfma_f32_16x16x32_bf16 v[124:127], v[128:131], v[162:165], v[124:127]
	v_mfma_f32_16x16x32_bf16 v[120:123], v[136:139], v[162:165], v[120:123]
	v_mfma_f32_16x16x32_bf16 v[116:119], v[128:131], v[180:183], v[116:119]
	v_mfma_f32_16x16x32_bf16 v[112:115], v[136:139], v[180:183], v[112:115]
	v_mfma_f32_16x16x32_bf16 v[108:111], v[128:131], v[188:191], v[108:111]
	v_mfma_f32_16x16x32_bf16 v[100:103], v[136:139], v[188:191], v[100:103]
	v_mfma_f32_16x16x32_bf16 v[92:95], v[128:131], v[196:199], v[92:95]
	v_mfma_f32_16x16x32_bf16 v[80:83], v[136:139], v[196:199], v[80:83]
	v_mfma_f32_16x16x32_bf16 v[124:127], v[132:135], v[176:179], v[124:127]
	v_mfma_f32_16x16x32_bf16 v[120:123], v[140:143], v[176:179], v[120:123]
	v_mfma_f32_16x16x32_bf16 v[116:119], v[132:135], v[184:187], v[116:119]
	v_mfma_f32_16x16x32_bf16 v[112:115], v[140:143], v[184:187], v[112:115]
	v_mfma_f32_16x16x32_bf16 v[108:111], v[132:135], v[192:195], v[108:111]
	v_mfma_f32_16x16x32_bf16 v[100:103], v[140:143], v[192:195], v[100:103]
	v_mfma_f32_16x16x32_bf16 v[92:95], v[132:135], v[200:203], v[92:95]
	v_mfma_f32_16x16x32_bf16 v[80:83], v[140:143], v[200:203], v[80:83]
	s_setprio 0
	s_barrier
; #define PG8_STAGE(bufoff, gbase, voff) do { _Pragma("unroll") for (int _i = 0; _i < 2; ++_i) \
;         __builtin_amdgcn_global_load_lds((const unsigned*)((const char*)(gbase) + (voff)[_i]), (LAS unsigned*)(lds + (bufoff) + ldsw + _i * 8192), 16, 0, 0); } while (0)
; #define PG8_LDA(dst, b, h) do { _Pragma("unroll") for (int m = 0; m < 4; ++m) _Pragma("unroll") for (int k = 0; k < 2; ++k) dst[m][k] = *(const LAS bf16x8*)(lds + PG8_SA(b, h) + aoff + m * 2048 + k * 1024); } while (0)
; #define PG8_LDB(dst, b, h) do { _Pragma("unroll") for (int n = 0; n < 2; ++n) _Pragma("unroll") for (int k = 0; k < 2; ++k) dst[n][k] = *(const LAS bf16x8*)(lds + PG8_SB(b, h) + boff + n * 2048 + k * 1024); } while (0)
; #define PG8_MMA(ai, bj, At, Bt) do { __builtin_amdgcn_s_setprio(1); _Pragma("unroll") for (int m = 0; m < 4; ++m) _Pragma("unroll") for (int n = 0; n < 2; ++n) _Pragma("unroll") for (int k = 0; k < 2; ++k) \
;         acc[ai][bj][m][n] = __builtin_amdgcn_mfma_f32_16x16x32_bf16(Bt[n][k], At[m][k], acc[ai][bj][m][n], 0, 0, 0); __builtin_amdgcn_s_setprio(0); } while (0)
; #define PG8_WAIT_V(n) asm volatile("s_waitcnt vmcnt(" #n ")" ::: "memory")
; #define PG8_WAIT_L(n) asm volatile("s_waitcnt lgkmcnt(" #n ")" ::: "memory")
; #define PG8_BAR __builtin_amdgcn_s_barrier()
; #define PG8_SCHED __builtin_amdgcn_sched_barrier(0)
;     ...
;             PG8_LDB(B1, 0, 1); PG8_STAGE(PG8_SB(0, 0), b2, voffB);
;             PG8_BAR; PG8_WAIT_L(0); PG8_MMA(0, 1, At, B1); PG8_BAR;
;             PG8_LDA(At, 0, 1); PG8_STAGE(PG8_SA(0, 0), a2, voffA);
;             PG8_BAR; PG8_WAIT_L(0); PG8_MMA(1, 0, At, B0); PG8_BAR; PG8_SCHED;
;             PG8_STAGE(PG8_SB(0, 1), b2 + hB, voffB);
;             PG8_WAIT_V(6); PG8_BAR; PG8_MMA(1, 1, At, B1); PG8_BAR;
;             PG8_LDB(B0, 1, 0); PG8_SCHED; PG8_LDA(At, 1, 0); PG8_STAGE(PG8_SA(0, 1), a2 + hA, voffA);
;             PG8_WAIT_L(8); PG8_BAR; PG8_WAIT_L(0); PG8_MMA(0, 0, At, B0); PG8_BAR; PG8_SCHED;
	s_add_i32 s45, s61, s42
	v_lshl_add_u64 v[220:221], s[36:37], 0, v[150:151]
	s_mov_b32 m0, s45
	ds_read_b128 v[204:207], v174
	ds_read_b128 v[208:211], v174 offset:1024
	ds_read_b128 v[212:215], v174 offset:2048
	ds_read_b128 v[216:219], v174 offset:3072
	global_load_lds_dwordx4 v[220:221], off
	v_lshl_add_u64 v[222:223], s[36:37], 0, v[146:147]
	s_add_i32 m0, s45, 0x2000
	s_nop 0
	global_load_lds_dwordx4 v[222:223], off
	s_barrier
	s_waitcnt lgkmcnt(0)
	s_setprio 1
	s_waitcnt lgkmcnt(0)
	v_mfma_f32_16x16x32_bf16 v[104:107], v[204:207], v[162:165], v[104:107]
	v_mfma_f32_16x16x32_bf16 v[96:99], v[212:215], v[162:165], v[96:99]
	v_mfma_f32_16x16x32_bf16 v[88:91], v[204:207], v[180:183], v[88:91]
	v_mfma_f32_16x16x32_bf16 v[84:87], v[212:215], v[180:183], v[84:87]
	v_mfma_f32_16x16x32_bf16 v[76:79], v[204:207], v[188:191], v[76:79]
	v_mfma_f32_16x16x32_bf16 v[72:75], v[212:215], v[188:191], v[72:75]
	v_mfma_f32_16x16x32_bf16 v[68:71], v[204:207], v[196:199], v[68:71]
	v_mfma_f32_16x16x32_bf16 v[64:67], v[212:215], v[196:199], v[64:67]
	v_mfma_f32_16x16x32_bf16 v[104:107], v[208:211], v[176:179], v[104:107]
	v_mfma_f32_16x16x32_bf16 v[96:99], v[216:219], v[176:179], v[96:99]
	v_mfma_f32_16x16x32_bf16 v[88:91], v[208:211], v[184:187], v[88:91]
	v_mfma_f32_16x16x32_bf16 v[84:87], v[216:219], v[184:187], v[84:87]
	v_mfma_f32_16x16x32_bf16 v[76:79], v[208:211], v[192:195], v[76:79]
	v_mfma_f32_16x16x32_bf16 v[72:75], v[216:219], v[192:195], v[72:75]
	v_mfma_f32_16x16x32_bf16 v[68:71], v[208:211], v[200:203], v[68:71]
	v_mfma_f32_16x16x32_bf16 v[64:67], v[216:219], v[200:203], v[64:67]
	s_setprio 0
	s_mov_b32 m0, s31
	v_lshl_add_u64 v[224:225], s[38:39], 0, v[152:153]
	s_barrier
	ds_read_b128 v[162:165], v173 offset:16384
	ds_read_b128 v[176:179], v173 offset:17408
	ds_read_b128 v[180:183], v173 offset:18432
	ds_read_b128 v[184:187], v173 offset:19456
	ds_read_b128 v[188:191], v173 offset:20480
	ds_read_b128 v[192:195], v173 offset:21504
	ds_read_b128 v[196:199], v173 offset:22528
	ds_read_b128 v[200:203], v173 offset:23552
	global_load_lds_dwordx4 v[224:225], off
	v_lshl_add_u64 v[226:227], s[38:39], 0, v[148:149]
	s_mov_b32 m0, s54
	s_nop 0
	global_load_lds_dwordx4 v[226:227], off
	s_barrier
	s_waitcnt lgkmcnt(0)
	s_setprio 1
	s_waitcnt lgkmcnt(0)
	v_mfma_f32_16x16x32_bf16 v[60:63], v[128:131], v[162:165], v[60:63]
	v_mfma_f32_16x16x32_bf16 v[56:59], v[136:139], v[162:165], v[56:59]
	v_mfma_f32_16x16x32_bf16 v[48:51], v[128:131], v[180:183], v[48:51]
	v_mfma_f32_16x16x32_bf16 v[40:43], v[136:139], v[180:183], v[40:43]
	v_mfma_f32_16x16x32_bf16 v[32:35], v[128:131], v[188:191], v[32:35]
	v_mfma_f32_16x16x32_bf16 v[24:27], v[136:139], v[188:191], v[24:27]
	v_mfma_f32_16x16x32_bf16 v[16:19], v[128:131], v[196:199], v[16:19]
	v_mfma_f32_16x16x32_bf16 v[8:11], v[136:139], v[196:199], v[8:11]
	v_mfma_f32_16x16x32_bf16 v[60:63], v[132:135], v[176:179], v[60:63]
	v_mfma_f32_16x16x32_bf16 v[56:59], v[140:143], v[176:179], v[56:59]
	v_mfma_f32_16x16x32_bf16 v[48:51], v[132:135], v[184:187], v[48:51]
	v_mfma_f32_16x16x32_bf16 v[40:43], v[140:143], v[184:187], v[40:43]
	v_mfma_f32_16x16x32_bf16 v[32:35], v[132:135], v[192:195], v[32:35]
	v_mfma_f32_16x16x32_bf16 v[24:27], v[140:143], v[192:195], v[24:27]
	v_mfma_f32_16x16x32_bf16 v[16:19], v[132:135], v[200:203], v[16:19]
	v_mfma_f32_16x16x32_bf16 v[8:11], v[140:143], v[200:203], v[8:11]
	s_setprio 0
	s_barrier
	s_add_u32 s64, s36, 0x20000
	s_addc_u32 s65, s37, 0
	s_add_i32 s45, s62, s42
	v_lshl_add_u64 v[128:129], s[64:65], 0, v[150:151]
	s_mov_b32 m0, s45
	s_nop 0
	global_load_lds_dwordx4 v[128:129], off
	v_lshl_add_u64 v[128:129], s[64:65], 0, v[146:147]
	s_add_i32 m0, s45, 0x2000
	s_nop 0
	global_load_lds_dwordx4 v[128:129], off
	s_waitcnt vmcnt(6)
	s_barrier
	s_setprio 1
	v_mfma_f32_16x16x32_bf16 v[52:55], v[204:207], v[162:165], v[52:55]
	v_mfma_f32_16x16x32_bf16 v[44:47], v[212:215], v[162:165], v[44:47]
	v_mfma_f32_16x16x32_bf16 v[36:39], v[204:207], v[180:183], v[36:39]
	v_mfma_f32_16x16x32_bf16 v[28:31], v[212:215], v[180:183], v[28:31]
	v_mfma_f32_16x16x32_bf16 v[20:23], v[204:207], v[188:191], v[20:23]
	v_mfma_f32_16x16x32_bf16 v[12:15], v[212:215], v[188:191], v[12:15]
	v_mfma_f32_16x16x32_bf16 v[4:7], v[204:207], v[196:199], v[4:7]
	v_mfma_f32_16x16x32_bf16 v[0:3], v[212:215], v[196:199], v[0:3]
	v_mfma_f32_16x16x32_bf16 v[52:55], v[208:211], v[176:179], v[52:55]
	v_mfma_f32_16x16x32_bf16 v[44:47], v[216:219], v[176:179], v[44:47]
	v_mfma_f32_16x16x32_bf16 v[36:39], v[208:211], v[184:187], v[36:39]
	v_mfma_f32_16x16x32_bf16 v[28:31], v[216:219], v[184:187], v[28:31]
	v_mfma_f32_16x16x32_bf16 v[20:23], v[208:211], v[192:195], v[20:23]
	v_mfma_f32_16x16x32_bf16 v[12:15], v[216:219], v[192:195], v[12:15]
	v_mfma_f32_16x16x32_bf16 v[4:7], v[208:211], v[200:203], v[4:7]
	v_mfma_f32_16x16x32_bf16 v[0:3], v[216:219], v[200:203], v[0:3]
	s_setprio 0
	s_add_i32 s45, 0, 0x18000
	v_add_u32_e32 v140, s45, v170
	s_barrier
	ds_read_b128 v[128:131], v140
	ds_read_b128 v[132:135], v140 offset:1024
	ds_read_b128 v[136:139], v140 offset:2048
	ds_read_b128 v[140:143], v140 offset:3072
	s_add_u32 s38, s38, 0x20000
	s_addc_u32 s39, s39, 0
	s_mov_b32 m0, s55
	v_lshl_add_u64 v[204:205], s[38:39], 0, v[152:153]
	ds_read_b128 v[162:165], v173 offset:32768
	ds_read_b128 v[176:179], v173 offset:33792
	ds_read_b128 v[180:183], v173 offset:34816
	ds_read_b128 v[184:187], v173 offset:35840
	ds_read_b128 v[188:191], v173 offset:36864
	ds_read_b128 v[192:195], v173 offset:37888
	ds_read_b128 v[196:199], v173 offset:38912
	ds_read_b128 v[200:203], v173 offset:39936
	global_load_lds_dwordx4 v[204:205], off
	v_lshl_add_u64 v[204:205], s[38:39], 0, v[148:149]
	s_mov_b32 m0, s56
	s_nop 0
	global_load_lds_dwordx4 v[204:205], off
	s_waitcnt lgkmcnt(8)
	s_barrier
; #define PG8_STAGE(bufoff, gbase, voff) do { _Pragma("unroll") for (int _i = 0; _i < 2; ++_i) \
;         __builtin_amdgcn_global_load_lds((const unsigned*)((const char*)(gbase) + (voff)[_i]), (LAS unsigned*)(lds + (bufoff) + ldsw + _i * 8192), 16, 0, 0); } while (0)
; #define PG8_LDA(dst, b, h) do { _Pragma("unroll") for (int m = 0; m < 4; ++m) _Pragma("unroll") for (int k = 0; k < 2; ++k) dst[m][k] = *(const LAS bf16x8*)(lds + PG8_SA(b, h) + aoff + m * 2048 + k * 1024); } while (0)
; #define PG8_LDB(dst, b, h) do { _Pragma("unroll") for (int n = 0; n < 2; ++n) _Pragma("unroll") for (int k = 0; k < 2; ++k) dst[n][k] = *(const LAS bf16x8*)(lds + PG8_SB(b, h) + boff + n * 2048 + k * 1024); } while (0)
; #define PG8_MMA(ai, bj, At, Bt) do { __builtin_amdgcn_s_setprio(1); _Pragma("unroll") for (int m = 0; m < 4; ++m) _Pragma("unroll") for (int n = 0; n < 2; ++n) _Pragma("unroll") for (int k = 0; k < 2; ++k) \
;         acc[ai][bj][m][n] = __builtin_amdgcn_mfma_f32_16x16x32_bf16(Bt[n][k], At[m][k], acc[ai][bj][m][n], 0, 0, 0); __builtin_amdgcn_s_setprio(0); } while (0)
; #define PG8_WAIT_V(n) asm volatile("s_waitcnt vmcnt(" #n ")" ::: "memory")
; #define PG8_WAIT_L(n) asm volatile("s_waitcnt lgkmcnt(" #n ")" ::: "memory")
; #define PG8_BAR __builtin_amdgcn_s_barrier()
; #define PG8_SCHED __builtin_amdgcn_sched_barrier(0)
;     ...
;             PG8_WAIT_L(8); PG8_BAR; PG8_WAIT_L(0); PG8_MMA(0, 0, At, B0); PG8_BAR; PG8_SCHED;
;             PG8_LDB(B1, 1, 1); PG8_STAGE(PG8_SB(1, 0), b3, voffB);
;             PG8_BAR; PG8_WAIT_L(0); PG8_MMA(0, 1, At, B1); PG8_BAR;
;             PG8_LDA(At, 1, 1); PG8_STAGE(PG8_SA(1, 0), a3, voffA);
;             PG8_BAR; PG8_WAIT_L(0); PG8_MMA(1, 0, At, B0); PG8_BAR; PG8_SCHED;
;             PG8_STAGE(PG8_SB(1, 1), b3 + hB, voffB);
;             PG8_WAIT_V(6); PG8_BAR; PG8_MMA(1, 1, At, B1); PG8_BAR;
	s_waitcnt lgkmcnt(0)
	s_setprio 1
	s_waitcnt lgkmcnt(0)
	v_mfma_f32_16x16x32_bf16 v[124:127], v[128:131], v[162:165], v[124:127]
	v_mfma_f32_16x16x32_bf16 v[120:123], v[136:139], v[162:165], v[120:123]
	v_mfma_f32_16x16x32_bf16 v[116:119], v[128:131], v[180:183], v[116:119]
	v_mfma_f32_16x16x32_bf16 v[112:115], v[136:139], v[180:183], v[112:115]
	v_mfma_f32_16x16x32_bf16 v[108:111], v[128:131], v[188:191], v[108:111]
	v_mfma_f32_16x16x32_bf16 v[100:103], v[136:139], v[188:191], v[100:103]
	v_mfma_f32_16x16x32_bf16 v[92:95], v[128:131], v[196:199], v[92:95]
	v_mfma_f32_16x16x32_bf16 v[80:83], v[136:139], v[196:199], v[80:83]
	v_mfma_f32_16x16x32_bf16 v[124:127], v[132:135], v[176:179], v[124:127]
	v_mfma_f32_16x16x32_bf16 v[120:123], v[140:143], v[176:179], v[120:123]
	v_mfma_f32_16x16x32_bf16 v[116:119], v[132:135], v[184:187], v[116:119]
	v_mfma_f32_16x16x32_bf16 v[112:115], v[140:143], v[184:187], v[112:115]
	v_mfma_f32_16x16x32_bf16 v[108:111], v[132:135], v[192:195], v[108:111]
	v_mfma_f32_16x16x32_bf16 v[100:103], v[140:143], v[192:195], v[100:103]
	v_mfma_f32_16x16x32_bf16 v[92:95], v[132:135], v[200:203], v[92:95]
	v_mfma_f32_16x16x32_bf16 v[80:83], v[140:143], v[200:203], v[80:83]
	s_setprio 0
	s_barrier
	s_add_i32 s38, 0, 0x1c000
	s_add_i32 s39, s45, s42
	v_add_u32_e32 v175, s38, v170
	v_lshl_add_u64 v[220:221], v[220:221], 0, s[20:21]
	s_mov_b32 m0, s39
	ds_read_b128 v[204:207], v175
	ds_read_b128 v[208:211], v175 offset:1024
	ds_read_b128 v[212:215], v175 offset:2048
	ds_read_b128 v[216:219], v175 offset:3072
	global_load_lds_dwordx4 v[220:221], off
	v_lshl_add_u64 v[220:221], v[222:223], 0, s[20:21]
	s_add_i32 m0, s39, 0x2000
	s_nop 0
	global_load_lds_dwordx4 v[220:221], off
	s_barrier
	s_waitcnt lgkmcnt(0)
	s_setprio 1
	s_waitcnt lgkmcnt(0)
	v_mfma_f32_16x16x32_bf16 v[104:107], v[204:207], v[162:165], v[104:107]
	v_mfma_f32_16x16x32_bf16 v[96:99], v[212:215], v[162:165], v[96:99]
	v_mfma_f32_16x16x32_bf16 v[88:91], v[204:207], v[180:183], v[88:91]
	v_mfma_f32_16x16x32_bf16 v[84:87], v[212:215], v[180:183], v[84:87]
	v_mfma_f32_16x16x32_bf16 v[76:79], v[204:207], v[188:191], v[76:79]
	v_mfma_f32_16x16x32_bf16 v[72:75], v[212:215], v[188:191], v[72:75]
	v_mfma_f32_16x16x32_bf16 v[68:71], v[204:207], v[196:199], v[68:71]
	v_mfma_f32_16x16x32_bf16 v[64:67], v[212:215], v[196:199], v[64:67]
	v_mfma_f32_16x16x32_bf16 v[104:107], v[208:211], v[176:179], v[104:107]
	v_mfma_f32_16x16x32_bf16 v[96:99], v[216:219], v[176:179], v[96:99]
	v_mfma_f32_16x16x32_bf16 v[88:91], v[208:211], v[184:187], v[88:91]
	v_mfma_f32_16x16x32_bf16 v[84:87], v[216:219], v[184:187], v[84:87]
	v_mfma_f32_16x16x32_bf16 v[76:79], v[208:211], v[192:195], v[76:79]
	v_mfma_f32_16x16x32_bf16 v[72:75], v[216:219], v[192:195], v[72:75]
	v_mfma_f32_16x16x32_bf16 v[68:71], v[208:211], v[200:203], v[68:71]
	v_mfma_f32_16x16x32_bf16 v[64:67], v[216:219], v[200:203], v[64:67]
	s_setprio 0
	s_mov_b32 m0, s57
	v_lshl_add_u64 v[220:221], v[224:225], 0, s[20:21]
	s_barrier
	ds_read_b128 v[162:165], v173 offset:49152
	ds_read_b128 v[176:179], v173 offset:50176
	ds_read_b128 v[180:183], v173 offset:51200
	ds_read_b128 v[184:187], v173 offset:52224
	ds_read_b128 v[188:191], v173 offset:53248
	ds_read_b128 v[192:195], v173 offset:54272
	ds_read_b128 v[196:199], v173 offset:55296
	ds_read_b128 v[200:203], v173 offset:56320
	global_load_lds_dwordx4 v[220:221], off
	v_lshl_add_u64 v[220:221], v[226:227], 0, s[20:21]
	s_mov_b32 m0, s58
	s_nop 0
	global_load_lds_dwordx4 v[220:221], off
	s_barrier
	s_waitcnt lgkmcnt(0)
	s_setprio 1
	s_waitcnt lgkmcnt(0)
	v_mfma_f32_16x16x32_bf16 v[60:63], v[128:131], v[162:165], v[60:63]
	v_mfma_f32_16x16x32_bf16 v[56:59], v[136:139], v[162:165], v[56:59]
	v_mfma_f32_16x16x32_bf16 v[48:51], v[128:131], v[180:183], v[48:51]
	v_mfma_f32_16x16x32_bf16 v[40:43], v[136:139], v[180:183], v[40:43]
	v_mfma_f32_16x16x32_bf16 v[32:35], v[128:131], v[188:191], v[32:35]
	v_mfma_f32_16x16x32_bf16 v[24:27], v[136:139], v[188:191], v[24:27]
	v_mfma_f32_16x16x32_bf16 v[16:19], v[128:131], v[196:199], v[16:19]
	v_mfma_f32_16x16x32_bf16 v[8:11], v[136:139], v[196:199], v[8:11]
	v_mfma_f32_16x16x32_bf16 v[60:63], v[132:135], v[176:179], v[60:63]
	v_mfma_f32_16x16x32_bf16 v[56:59], v[140:143], v[176:179], v[56:59]
	v_mfma_f32_16x16x32_bf16 v[48:51], v[132:135], v[184:187], v[48:51]
	v_mfma_f32_16x16x32_bf16 v[40:43], v[140:143], v[184:187], v[40:43]
	v_mfma_f32_16x16x32_bf16 v[32:35], v[132:135], v[192:195], v[32:35]
	v_mfma_f32_16x16x32_bf16 v[24:27], v[140:143], v[192:195], v[24:27]
	v_mfma_f32_16x16x32_bf16 v[16:19], v[132:135], v[200:203], v[16:19]
	v_mfma_f32_16x16x32_bf16 v[8:11], v[140:143], v[200:203], v[8:11]
	s_setprio 0
	s_barrier
	s_add_u32 s36, s36, 0x20080
	s_addc_u32 s37, s37, 0
	s_add_i32 s38, s38, s42
	v_lshl_add_u64 v[128:129], s[36:37], 0, v[150:151]
	s_mov_b32 m0, s38
	s_nop 0
	global_load_lds_dwordx4 v[128:129], off
	v_lshl_add_u64 v[128:129], s[36:37], 0, v[146:147]
	s_add_i32 m0, s38, 0x2000
	s_nop 0
	global_load_lds_dwordx4 v[128:129], off
	s_waitcnt vmcnt(6)
	s_barrier
; #define PG8_MMA(ai, bj, At, Bt) do { __builtin_amdgcn_s_setprio(1); _Pragma("unroll") for (int m = 0; m < 4; ++m) _Pragma("unroll") for (int n = 0; n < 2; ++n) _Pragma("unroll") for (int k = 0; k < 2; ++k) \
;         acc[ai][bj][m][n] = __builtin_amdgcn_mfma_f32_16x16x32_bf16(Bt[n][k], At[m][k], acc[ai][bj][m][n], 0, 0, 0); __builtin_amdgcn_s_setprio(0); } while (0)
; #define PG8_WAIT_V(n) asm volatile("s_waitcnt vmcnt(" #n ")" ::: "memory")
; #define PG8_BAR __builtin_amdgcn_s_barrier()
;     ...
;             PG8_WAIT_V(6); PG8_BAR; PG8_MMA(1, 1, At, B1); PG8_BAR;
;         }
;         E(acc, cur, wr, wc, fr, fq);
;     __device__ __forceinline__ void operator()(const f32x4 (&acc)[2][2][4][2], const Unit& u, int wr, int wc, int fr, int fq) const {
;         const int row0 = u.pm * 256 + wr * 64 + fr, col0 = u.pn * 256 + wc * 32 + 8 * fq;
;         f32x4 bv[2][2];
; #pragma unroll
;         for (int bj = 0; bj < 2; ++bj)
; #pragma unroll
;             for (int n = 0; n < 2; ++n) bv[bj][n] = *(const f32x4*)(scale + col0 + bj * 128 + 4 * n);
	s_setprio 1
	v_mfma_f32_16x16x32_bf16 v[52:55], v[204:207], v[162:165], v[52:55]
	v_mfma_f32_16x16x32_bf16 v[44:47], v[212:215], v[162:165], v[44:47]
	v_mfma_f32_16x16x32_bf16 v[36:39], v[204:207], v[180:183], v[36:39]
	v_mfma_f32_16x16x32_bf16 v[28:31], v[212:215], v[180:183], v[28:31]
	v_mfma_f32_16x16x32_bf16 v[20:23], v[204:207], v[188:191], v[20:23]
	v_mfma_f32_16x16x32_bf16 v[12:15], v[212:215], v[188:191], v[12:15]
	v_mfma_f32_16x16x32_bf16 v[4:7], v[204:207], v[196:199], v[4:7]
	v_mfma_f32_16x16x32_bf16 v[0:3], v[212:215], v[196:199], v[0:3]
	v_mfma_f32_16x16x32_bf16 v[52:55], v[208:211], v[176:179], v[52:55]
	v_mfma_f32_16x16x32_bf16 v[44:47], v[216:219], v[176:179], v[44:47]
	v_mfma_f32_16x16x32_bf16 v[36:39], v[208:211], v[184:187], v[36:39]
	v_mfma_f32_16x16x32_bf16 v[28:31], v[216:219], v[184:187], v[28:31]
	v_mfma_f32_16x16x32_bf16 v[20:23], v[208:211], v[192:195], v[20:23]
	v_mfma_f32_16x16x32_bf16 v[12:15], v[216:219], v[192:195], v[12:15]
	v_mfma_f32_16x16x32_bf16 v[4:7], v[208:211], v[200:203], v[4:7]
	v_mfma_f32_16x16x32_bf16 v[0:3], v[216:219], v[200:203], v[0:3]
	s_setprio 0
	s_add_i32 s44, s44, 2
	s_add_u32 s25, s25, 0x100
	s_addc_u32 s33, s33, 0
	s_add_u32 s34, s34, 0x100
	s_addc_u32 s35, s35, 0
	s_cmp_gt_u32 s44, 1
	s_barrier
	s_cbranch_scc0 .LBB0_1485
	v_lshl_or_b32 v164, s6, 8, v171
	v_ashrrev_i32_e32 v165, 31, v164
	v_lshl_add_u64 v[128:129], v[164:165], 2, s[18:19]
	global_load_dwordx4 v[140:143], v[128:129], off offset:2048
	global_load_dwordx4 v[136:139], v[128:129], off offset:2064
	global_load_dwordx4 v[132:135], v[128:129], off offset:2560
	s_nop 0
	global_load_dwordx4 v[128:131], v[128:129], off offset:2576
	v_lshl_add_u32 v175, s30, 8, v169
	v_mov_b64_e32 v[162:163], s[16:17]
	v_mad_i64_i32 v[176:177], s[6:7], v175, s63, v[162:163]
	v_lshlrev_b64 v[164:165], 1, v[164:165]
	v_or_b32_e32 v178, 16, v175
	v_lshl_add_u64 v[176:177], v[176:177], 0, v[164:165]
	v_mad_i64_i32 v[178:179], s[6:7], v178, s63, v[162:163]
	v_or_b32_e32 v180, 32, v175
	v_lshl_add_u64 v[178:179], v[178:179], 0, v[164:165]
	v_mad_i64_i32 v[180:181], s[6:7], v180, s63, v[162:163]
	v_or_b32_e32 v182, 48, v175
	v_lshl_add_u64 v[180:181], v[180:181], 0, v[164:165]
	v_mad_i64_i32 v[182:183], s[6:7], v182, s63, v[162:163]
	v_lshl_add_u64 v[182:183], v[182:183], 0, v[164:165]
	s_and_b64 vcc, exec, s[10:11]
	s_mov_b32 s30, s24
	s_mov_b64 s[34:35], s[28:29]
	s_mov_b64 s[36:37], s[26:27]
	s_waitcnt vmcnt(0)
; __device__ __forceinline__ u32x4 pack8(const f32x4 v0, const f32x4 v1) { u32x4 w; w.x = pk2(v0[0], v0[1]); w.y = pk2(v0[2], v0[3]); w.z = pk2(v1[0], v1[1]); w.w = pk2(v1[2], v1[3]); return w; }
;     __device__ __forceinline__ void operator()(const f32x4 (&acc)[2][2][4][2], const Unit& u, int wr, int wc, int fr, int fq) const {
;     ...
; #pragma unroll
;         for (int ai = 0; ai < 2; ++ai)
; #pragma unroll
;             for (int m = 0; m < 4; ++m) {
;                 bf16_t* rowp = z + (size_t)(row0 + ai * 128 + m * 16) * DIN + O_U + col0;
; #pragma unroll
;                 for (int bj = 0; bj < 2; ++bj) *(u32x4*)(rowp + bj * 128) = pack8(acc[ai][bj][m][0] * bv[bj][0], acc[ai][bj][m][1] * bv[bj][1]);
;             }
	v_pk_mul_f32 v[124:125], v[124:125], v[140:141]
	v_pk_mul_f32 v[126:127], v[126:127], v[142:143]
	v_pk_mul_f32 v[122:123], v[122:123], v[138:139]
	v_pk_mul_f32 v[186:187], v[64:65], v[128:129]
	v_cvt_pk_bf16_f32 v64, v124, v125
	v_pk_mul_f32 v[120:121], v[120:121], v[136:137]
	v_pk_mul_f32 v[104:105], v[104:105], v[132:133]
	v_pk_mul_f32 v[184:185], v[66:67], v[130:131]
	v_cvt_pk_bf16_f32 v65, v126, v127
	v_cvt_pk_bf16_f32 v66, v120, v121
	v_cvt_pk_bf16_f32 v67, v122, v123
	global_store_dwordx4 v[176:177], v[64:67], off offset:3584 sc1
	v_pk_mul_f32 v[106:107], v[106:107], v[134:135]
	v_pk_mul_f32 v[98:99], v[98:99], v[130:131]
	v_cvt_pk_bf16_f32 v64, v104, v105
	v_pk_mul_f32 v[96:97], v[96:97], v[128:129]
	v_pk_mul_f32 v[116:117], v[116:117], v[140:141]
	v_cvt_pk_bf16_f32 v65, v106, v107
	v_cvt_pk_bf16_f32 v66, v96, v97
	v_cvt_pk_bf16_f32 v67, v98, v99
	global_store_dwordx4 v[176:177], v[64:67], off offset:3840 sc1
	v_pk_mul_f32 v[118:119], v[118:119], v[142:143]
	v_pk_mul_f32 v[114:115], v[114:115], v[138:139]
	v_cvt_pk_bf16_f32 v64, v116, v117
	v_pk_mul_f32 v[112:113], v[112:113], v[136:137]
	v_pk_mul_f32 v[88:89], v[88:89], v[132:133]
	v_cvt_pk_bf16_f32 v65, v118, v119
	v_cvt_pk_bf16_f32 v66, v112, v113
	v_cvt_pk_bf16_f32 v67, v114, v115
	global_store_dwordx4 v[178:179], v[64:67], off offset:3584 sc1
	v_pk_mul_f32 v[90:91], v[90:91], v[134:135]
	v_pk_mul_f32 v[86:87], v[86:87], v[130:131]
	v_cvt_pk_bf16_f32 v64, v88, v89
	v_pk_mul_f32 v[84:85], v[84:85], v[128:129]
	v_pk_mul_f32 v[108:109], v[108:109], v[140:141]
	v_cvt_pk_bf16_f32 v65, v90, v91
	v_cvt_pk_bf16_f32 v66, v84, v85
	v_cvt_pk_bf16_f32 v67, v86, v87
	global_store_dwordx4 v[178:179], v[64:67], off offset:3840 sc1
	v_pk_mul_f32 v[110:111], v[110:111], v[142:143]
	v_pk_mul_f32 v[102:103], v[102:103], v[138:139]
	v_cvt_pk_bf16_f32 v64, v108, v109
	v_pk_mul_f32 v[100:101], v[100:101], v[136:137]
	v_pk_mul_f32 v[76:77], v[76:77], v[132:133]
	v_cvt_pk_bf16_f32 v65, v110, v111
	v_cvt_pk_bf16_f32 v66, v100, v101
	v_cvt_pk_bf16_f32 v67, v102, v103
	global_store_dwordx4 v[180:181], v[64:67], off offset:3584 sc1
	v_pk_mul_f32 v[78:79], v[78:79], v[134:135]
	v_pk_mul_f32 v[74:75], v[74:75], v[130:131]
	v_cvt_pk_bf16_f32 v64, v76, v77
	v_pk_mul_f32 v[72:73], v[72:73], v[128:129]
	v_pk_mul_f32 v[92:93], v[92:93], v[140:141]
	v_cvt_pk_bf16_f32 v65, v78, v79
	v_cvt_pk_bf16_f32 v66, v72, v73
	v_cvt_pk_bf16_f32 v67, v74, v75
	global_store_dwordx4 v[180:181], v[64:67], off offset:3840 sc1
	v_pk_mul_f32 v[94:95], v[94:95], v[142:143]
	v_pk_mul_f32 v[82:83], v[82:83], v[138:139]
	v_cvt_pk_bf16_f32 v64, v92, v93
	v_pk_mul_f32 v[80:81], v[80:81], v[136:137]
	v_pk_mul_f32 v[68:69], v[68:69], v[132:133]
	v_cvt_pk_bf16_f32 v65, v94, v95
	v_cvt_pk_bf16_f32 v66, v80, v81
	v_cvt_pk_bf16_f32 v67, v82, v83
	global_store_dwordx4 v[182:183], v[64:67], off offset:3584 sc1
	v_pk_mul_f32 v[70:71], v[70:71], v[134:135]
	v_pk_mul_f32 v[62:63], v[62:63], v[142:143]
	v_cvt_pk_bf16_f32 v64, v68, v69
	v_cvt_pk_bf16_f32 v65, v70, v71
	v_cvt_pk_bf16_f32 v66, v186, v187
	v_cvt_pk_bf16_f32 v67, v184, v185
	global_store_dwordx4 v[182:183], v[64:67], off offset:3840 sc1
	v_pk_mul_f32 v[60:61], v[60:61], v[140:141]
	v_pk_mul_f32 v[52:53], v[52:53], v[132:133]
	v_add_u32_e32 v64, 0x80, v175
	v_mad_i64_i32 v[64:65], s[6:7], v64, s63, v[162:163]
	v_lshl_add_u64 v[64:65], v[64:65], 0, v[164:165]
	v_pk_mul_f32 v[66:67], v[58:59], v[138:139]
	v_pk_mul_f32 v[58:59], v[56:57], v[136:137]
	v_cvt_pk_bf16_f32 v56, v60, v61
	v_cvt_pk_bf16_f32 v57, v62, v63
	v_pk_mul_f32 v[54:55], v[54:55], v[134:135]
	v_cvt_pk_bf16_f32 v58, v58, v59
	v_cvt_pk_bf16_f32 v59, v66, v67
	global_store_dwordx4 v[64:65], v[56:59], off offset:3584 sc1
	v_pk_mul_f32 v[48:49], v[48:49], v[140:141]
	v_pk_mul_f32 v[36:37], v[36:37], v[132:133]
	v_pk_mul_f32 v[56:57], v[46:47], v[130:131]
	v_pk_mul_f32 v[46:47], v[44:45], v[128:129]
	v_cvt_pk_bf16_f32 v44, v52, v53
	v_cvt_pk_bf16_f32 v45, v54, v55
	v_pk_mul_f32 v[38:39], v[38:39], v[134:135]
	v_cvt_pk_bf16_f32 v46, v46, v47
	v_cvt_pk_bf16_f32 v47, v56, v57
	global_store_dwordx4 v[64:65], v[44:47], off offset:3840 sc1
	v_pk_mul_f32 v[32:33], v[32:33], v[140:141]
	v_pk_mul_f32 v[20:21], v[20:21], v[132:133]
	v_add_u32_e32 v44, 0x90, v175
	v_mad_i64_i32 v[44:45], s[6:7], v44, s63, v[162:163]
	v_lshl_add_u64 v[44:45], v[44:45], 0, v[164:165]
	v_pk_mul_f32 v[46:47], v[50:51], v[142:143]
	v_pk_mul_f32 v[50:51], v[42:43], v[138:139]
	v_pk_mul_f32 v[42:43], v[40:41], v[136:137]
	v_cvt_pk_bf16_f32 v40, v48, v49
	v_cvt_pk_bf16_f32 v41, v46, v47
	v_pk_mul_f32 v[22:23], v[22:23], v[134:135]
	v_cvt_pk_bf16_f32 v42, v42, v43
	v_cvt_pk_bf16_f32 v43, v50, v51
	global_store_dwordx4 v[44:45], v[40:43], off offset:3584 sc1
	v_pk_mul_f32 v[16:17], v[16:17], v[140:141]
	v_pk_mul_f32 v[6:7], v[6:7], v[134:135]
	v_pk_mul_f32 v[40:41], v[30:31], v[130:131]
	v_pk_mul_f32 v[30:31], v[28:29], v[128:129]
	v_cvt_pk_bf16_f32 v28, v36, v37
	v_cvt_pk_bf16_f32 v29, v38, v39
	v_pk_mul_f32 v[4:5], v[4:5], v[132:133]
	v_cvt_pk_bf16_f32 v30, v30, v31
	v_cvt_pk_bf16_f32 v31, v40, v41
	global_store_dwordx4 v[44:45], v[28:31], off offset:3840 sc1
	s_nop 1
	v_add_u32_e32 v28, 0xa0, v175
	v_mad_i64_i32 v[28:29], s[6:7], v28, s63, v[162:163]
	v_lshl_add_u64 v[28:29], v[28:29], 0, v[164:165]
	v_pk_mul_f32 v[30:31], v[34:35], v[142:143]
	v_pk_mul_f32 v[34:35], v[26:27], v[138:139]
	v_pk_mul_f32 v[26:27], v[24:25], v[136:137]
	v_cvt_pk_bf16_f32 v24, v32, v33
	v_cvt_pk_bf16_f32 v25, v30, v31
	s_nop 0
	v_cvt_pk_bf16_f32 v26, v26, v27
	v_cvt_pk_bf16_f32 v27, v34, v35
	global_store_dwordx4 v[28:29], v[24:27], off offset:3584 sc1
	s_nop 1
	v_pk_mul_f32 v[24:25], v[14:15], v[130:131]
	v_pk_mul_f32 v[14:15], v[12:13], v[128:129]
	v_cvt_pk_bf16_f32 v12, v20, v21
	v_cvt_pk_bf16_f32 v13, v22, v23
	s_nop 0
	v_cvt_pk_bf16_f32 v14, v14, v15
	v_cvt_pk_bf16_f32 v15, v24, v25
	global_store_dwordx4 v[28:29], v[12:15], off offset:3840 sc1
	s_nop 1
	v_add_u32_e32 v12, 0xb0, v175
	v_mad_i64_i32 v[12:13], s[6:7], v12, s63, v[162:163]
	v_lshl_add_u64 v[12:13], v[12:13], 0, v[164:165]
	v_pk_mul_f32 v[14:15], v[18:19], v[142:143]
	v_pk_mul_f32 v[18:19], v[10:11], v[138:139]
	v_pk_mul_f32 v[10:11], v[8:9], v[136:137]
	v_cvt_pk_bf16_f32 v8, v16, v17
	v_cvt_pk_bf16_f32 v9, v14, v15
	s_mov_b32 s6, s22
	v_cvt_pk_bf16_f32 v10, v10, v11
	v_cvt_pk_bf16_f32 v11, v18, v19
	global_store_dwordx4 v[12:13], v[8:11], off offset:3584 sc1
	s_nop 1
	v_pk_mul_f32 v[8:9], v[2:3], v[130:131]
	v_pk_mul_f32 v[2:3], v[0:1], v[128:129]
	v_cvt_pk_bf16_f32 v0, v4, v5
	v_cvt_pk_bf16_f32 v1, v6, v7
	s_nop 0
	v_cvt_pk_bf16_f32 v2, v2, v3
	v_cvt_pk_bf16_f32 v3, v8, v9
	global_store_dwordx4 v[12:13], v[0:3], off offset:3840 sc1
	s_cbranch_vccz .LBB0_1482
	s_waitcnt vmcnt(0)
	s_cmpk_gt_u32 s41, 0xff
	s_cbranch_scc1 .LBB0_1489
	s_barrier
